# phase 0a weight transposes: both 16-load passes of a tile issued back to back (32 loads in flight, per-pass registers) in 7 of the 12 tile loops, on top of P5 prefetch
# baseline (speedup 1.0000x reference)
.LBB0_20:
	s_lshl_b32 s75, s2, 1
	s_lshl_b32 s76, s73, 1
	v_or_b32_e32 v158, s75, v1
	v_or_b32_e32 v159, s76, v2
	s_add_i32 s78, s76, 4
	s_add_i32 s77, s75, 4
	s_add_i32 s79, s75, 8
	s_add_i32 s80, s76, 8
	s_add_i32 s81, s75, 12
	s_add_i32 s83, s75, 16
	s_add_i32 s85, s75, 20
	s_add_i32 s87, s75, 24
	s_add_i32 s75, s75, 28
	v_add_lshl_u32 v6, v158, v3, 7
	v_add_lshl_u32 v38, v159, v34, 7
	v_or_b32_e32 v161, s78, v2
	s_add_i32 s82, s76, 12
	v_or_b32_e32 v160, s77, v1
	v_or_b32_e32 v162, s79, v1
	v_or_b32_e32 v163, s80, v2
	v_or_b32_e32 v164, s81, v1
	v_or_b32_e32 v166, s83, v1
	v_or_b32_e32 v168, s85, v1
	v_or_b32_e32 v170, s87, v1
	v_or_b32_e32 v172, s75, v1
	v_or_b32_e32 v36, v6, v35
	v_or_b32_e32 v6, v38, v35
	v_add_lshl_u32 v40, v161, v34, 7
	v_mov_b32_e32 v37, v7
	s_add_i32 s84, s76, 16
	v_or_b32_e32 v165, s82, v2
	v_add_lshl_u32 v38, v160, v3, 7
	v_add_lshl_u32 v42, v162, v3, 7
	v_add_lshl_u32 v84, v163, v34, 7
	v_add_lshl_u32 v44, v164, v3, 7
	v_add_lshl_u32 v58, v166, v3, 7
	v_add_lshl_u32 v60, v168, v3, 7
	v_add_lshl_u32 v62, v170, v3, 7
	v_add_lshl_u32 v66, v172, v3, 7
	v_lshl_add_u64 v[64:65], v[6:7], 2, s[18:19]
	v_or_b32_e32 v6, v40, v35
	v_mov_b32_e32 v39, v7
	s_add_i32 s86, s76, 20
	v_or_b32_e32 v167, s84, v2
	v_add_lshl_u32 v85, v165, v34, 7
	v_lshl_add_u64 v[36:37], v[36:37], 2, s[18:19]
	v_or_b32_e32 v38, v38, v35
	v_or_b32_e32 v40, v42, v35
	v_or_b32_e32 v42, v44, v35
	v_or_b32_e32 v44, v58, v35
	v_or_b32_e32 v58, v60, v35
	v_or_b32_e32 v60, v62, v35
	v_or_b32_e32 v62, v66, v35
	v_lshl_add_u64 v[66:67], v[6:7], 2, s[18:19]
	v_or_b32_e32 v6, v84, v35
	s_add_i32 s92, s76, 24
	v_or_b32_e32 v169, s86, v2
	v_add_lshl_u32 v86, v167, v34, 7
	v_lshl_add_u64 v[38:39], v[38:39], 2, s[18:19]
	global_load_dword v174, v[64:65], off
	global_load_dword v180, v[36:37], off
	global_load_dword v181, v[66:67], off
	global_load_dword v182, v[38:39], off
	v_lshl_add_u64 v[36:37], v[6:7], 2, s[18:19]
	v_or_b32_e32 v6, v85, v35
	v_mov_b32_e32 v41, v7
	v_mov_b32_e32 v43, v7
	s_add_i32 s76, s76, 28
	v_or_b32_e32 v171, s92, v2
	v_add_lshl_u32 v87, v169, v34, 7
	v_lshl_add_u64 v[38:39], v[6:7], 2, s[18:19]
	v_or_b32_e32 v6, v86, v35
	v_or_b32_e32 v173, s76, v2
	v_add_lshl_u32 v88, v171, v34, 7
	v_lshl_add_u64 v[40:41], v[40:41], 2, s[18:19]
	v_lshl_add_u64 v[42:43], v[42:43], 2, s[18:19]
	global_load_dword v175, v[36:37], off
	global_load_dword v176, v[40:41], off
	global_load_dword v183, v[38:39], off
	global_load_dword v184, v[42:43], off
	v_lshl_add_u64 v[36:37], v[6:7], 2, s[18:19]
	v_or_b32_e32 v6, v87, v35
	v_mov_b32_e32 v45, v7
	v_mov_b32_e32 v59, v7
	v_add_lshl_u32 v89, v173, v34, 7
	v_lshl_add_u64 v[38:39], v[6:7], 2, s[18:19]
	v_or_b32_e32 v6, v88, v35
	v_mov_b32_e32 v61, v7
	v_mov_b32_e32 v63, v7
	v_lshl_add_u64 v[44:45], v[44:45], 2, s[18:19]
	v_lshl_add_u64 v[58:59], v[58:59], 2, s[18:19]
	global_load_dword v177, v[36:37], off
	global_load_dword v178, v[44:45], off
	global_load_dword v185, v[38:39], off
	global_load_dword v186, v[58:59], off
	v_lshl_add_u64 v[36:37], v[6:7], 2, s[18:19]
	v_or_b32_e32 v6, v89, v35
	v_lshl_add_u64 v[60:61], v[60:61], 2, s[18:19]
	v_lshl_add_u64 v[62:63], v[62:63], 2, s[18:19]
	v_lshl_add_u64 v[38:39], v[6:7], 2, s[18:19]
	global_load_dword v157, v[36:37], off
	global_load_dword v179, v[60:61], off
	global_load_dword v187, v[38:39], off
	global_load_dword v188, v[62:63], off
	s_add_i32 s73, s73, 16
	s_add_i32 s2, s2, 16
	s_lshl_b32 s75, s2, 1
	s_lshl_b32 s76, s73, 1
	v_or_b32_e32 v190, s75, v1
	v_or_b32_e32 v191, s76, v2
	s_add_i32 s78, s76, 4
	s_add_i32 s77, s75, 4
	s_add_i32 s79, s75, 8
	s_add_i32 s80, s76, 8
	s_add_i32 s81, s75, 12
	s_add_i32 s83, s75, 16
	s_add_i32 s85, s75, 20
	s_add_i32 s87, s75, 24
	s_add_i32 s75, s75, 28
	v_add_lshl_u32 v6, v190, v3, 7
	v_add_lshl_u32 v38, v191, v34, 7
	v_or_b32_e32 v193, s78, v2
	s_add_i32 s82, s76, 12
	v_or_b32_e32 v192, s77, v1
	v_or_b32_e32 v194, s79, v1
	v_or_b32_e32 v195, s80, v2
	v_or_b32_e32 v196, s81, v1
	v_or_b32_e32 v198, s83, v1
	v_or_b32_e32 v200, s85, v1
	v_or_b32_e32 v202, s87, v1
	v_or_b32_e32 v204, s75, v1
	v_or_b32_e32 v36, v6, v35
	v_or_b32_e32 v6, v38, v35
	v_add_lshl_u32 v40, v193, v34, 7
	v_mov_b32_e32 v37, v7
	s_add_i32 s84, s76, 16
	v_or_b32_e32 v197, s82, v2
	v_add_lshl_u32 v38, v192, v3, 7
	v_add_lshl_u32 v42, v194, v3, 7
	v_add_lshl_u32 v84, v195, v34, 7
	v_add_lshl_u32 v44, v196, v3, 7
	v_add_lshl_u32 v58, v198, v3, 7
	v_add_lshl_u32 v60, v200, v3, 7
	v_add_lshl_u32 v62, v202, v3, 7
	v_add_lshl_u32 v66, v204, v3, 7
	v_lshl_add_u64 v[64:65], v[6:7], 2, s[18:19]
	v_or_b32_e32 v6, v40, v35
	v_mov_b32_e32 v39, v7
	s_add_i32 s86, s76, 20
	v_or_b32_e32 v199, s84, v2
	v_add_lshl_u32 v85, v197, v34, 7
	v_lshl_add_u64 v[36:37], v[36:37], 2, s[18:19]
	v_or_b32_e32 v38, v38, v35
	v_or_b32_e32 v40, v42, v35
	v_or_b32_e32 v42, v44, v35
	v_or_b32_e32 v44, v58, v35
	v_or_b32_e32 v58, v60, v35
	v_or_b32_e32 v60, v62, v35
	v_or_b32_e32 v62, v66, v35
	v_lshl_add_u64 v[66:67], v[6:7], 2, s[18:19]
	v_or_b32_e32 v6, v84, v35
	s_add_i32 s92, s76, 24
	v_or_b32_e32 v201, s86, v2
	v_add_lshl_u32 v86, v199, v34, 7
	v_lshl_add_u64 v[38:39], v[38:39], 2, s[18:19]
	global_load_dword v206, v[64:65], off
	global_load_dword v212, v[36:37], off
	global_load_dword v213, v[66:67], off
	global_load_dword v214, v[38:39], off
	v_lshl_add_u64 v[36:37], v[6:7], 2, s[18:19]
	v_or_b32_e32 v6, v85, v35
	v_mov_b32_e32 v41, v7
	v_mov_b32_e32 v43, v7
	s_add_i32 s76, s76, 28
	v_or_b32_e32 v203, s92, v2
	v_add_lshl_u32 v87, v201, v34, 7
	v_lshl_add_u64 v[38:39], v[6:7], 2, s[18:19]
	v_or_b32_e32 v6, v86, v35
	v_or_b32_e32 v205, s76, v2
	v_add_lshl_u32 v88, v203, v34, 7
	v_lshl_add_u64 v[40:41], v[40:41], 2, s[18:19]
	v_lshl_add_u64 v[42:43], v[42:43], 2, s[18:19]
	global_load_dword v207, v[36:37], off
	global_load_dword v208, v[40:41], off
	global_load_dword v215, v[38:39], off
	global_load_dword v216, v[42:43], off
	v_lshl_add_u64 v[36:37], v[6:7], 2, s[18:19]
	v_or_b32_e32 v6, v87, v35
	v_mov_b32_e32 v45, v7
	v_mov_b32_e32 v59, v7
	v_add_lshl_u32 v89, v205, v34, 7
	v_lshl_add_u64 v[38:39], v[6:7], 2, s[18:19]
	v_or_b32_e32 v6, v88, v35
	v_mov_b32_e32 v61, v7
	v_mov_b32_e32 v63, v7
	v_lshl_add_u64 v[44:45], v[44:45], 2, s[18:19]
	v_lshl_add_u64 v[58:59], v[58:59], 2, s[18:19]
	global_load_dword v209, v[36:37], off
	global_load_dword v210, v[44:45], off
	global_load_dword v217, v[38:39], off
	global_load_dword v218, v[58:59], off
	v_lshl_add_u64 v[36:37], v[6:7], 2, s[18:19]
	v_or_b32_e32 v6, v89, v35
	v_lshl_add_u64 v[60:61], v[60:61], 2, s[18:19]
	v_lshl_add_u64 v[62:63], v[62:63], 2, s[18:19]
	v_lshl_add_u64 v[38:39], v[6:7], 2, s[18:19]
	global_load_dword v189, v[36:37], off
	global_load_dword v211, v[60:61], off
	global_load_dword v219, v[38:39], off
	global_load_dword v221, v[62:63], off
	v_mad_u64_u32 v[36:37], s[76:77], v159, s3, v[4:5]
	v_mad_u64_u32 v[38:39], s[76:77], v158, s3, v[4:5]
	v_mad_u64_u32 v[40:41], s[76:77], v161, s3, v[4:5]
	v_mad_u64_u32 v[42:43], s[76:77], v160, s3, v[4:5]
	v_mad_u64_u32 v[44:45], s[76:77], v163, s3, v[4:5]
	v_mad_u64_u32 v[58:59], s[76:77], v162, s3, v[4:5]
	v_mad_u64_u32 v[60:61], s[76:77], v165, s3, v[4:5]
	v_mad_u64_u32 v[62:63], s[76:77], v164, s3, v[4:5]
	v_mad_u64_u32 v[64:65], s[76:77], v167, s3, v[4:5]
	v_mad_u64_u32 v[66:67], s[76:77], v166, s3, v[4:5]
	v_mad_u64_u32 v[68:69], s[76:77], v169, s3, v[4:5]
	v_mad_u64_u32 v[70:71], s[76:77], v168, s3, v[4:5]
	v_mad_u64_u32 v[72:73], s[76:77], v171, s3, v[4:5]
	v_mad_u64_u32 v[74:75], s[76:77], v170, s3, v[4:5]
	v_mad_u64_u32 v[76:77], s[76:77], v173, s3, v[4:5]
	v_mad_u64_u32 v[78:79], s[76:77], v172, s3, v[4:5]
	s_waitcnt vmcnt(31)
	ds_write_b32 v36, v174
	s_waitcnt vmcnt(30)
	ds_write_b32 v38, v180
	s_waitcnt vmcnt(29)
	ds_write_b32 v40, v181
	s_waitcnt vmcnt(28)
	ds_write_b32 v42, v182
	s_waitcnt vmcnt(27)
	ds_write_b32 v44, v175
	s_waitcnt vmcnt(26)
	ds_write_b32 v58, v176
	s_waitcnt vmcnt(25)
	ds_write_b32 v60, v183
	s_waitcnt vmcnt(24)
	ds_write_b32 v62, v184
	s_waitcnt vmcnt(23)
	ds_write_b32 v64, v177
	s_waitcnt vmcnt(22)
	ds_write_b32 v66, v178
	s_waitcnt vmcnt(21)
	ds_write_b32 v68, v185
	s_waitcnt vmcnt(20)
	ds_write_b32 v70, v186
	s_waitcnt vmcnt(19)
	ds_write_b32 v72, v157
	s_waitcnt vmcnt(18)
	ds_write_b32 v74, v179
	s_waitcnt vmcnt(17)
	ds_write_b32 v76, v187
	s_waitcnt vmcnt(16)
	ds_write_b32 v78, v188
	v_mad_u64_u32 v[36:37], s[76:77], v191, s3, v[4:5]
	v_mad_u64_u32 v[38:39], s[76:77], v190, s3, v[4:5]
	v_mad_u64_u32 v[40:41], s[76:77], v193, s3, v[4:5]
	v_mad_u64_u32 v[42:43], s[76:77], v192, s3, v[4:5]
	v_mad_u64_u32 v[44:45], s[76:77], v195, s3, v[4:5]
	v_mad_u64_u32 v[58:59], s[76:77], v194, s3, v[4:5]
	v_mad_u64_u32 v[60:61], s[76:77], v197, s3, v[4:5]
	v_mad_u64_u32 v[62:63], s[76:77], v196, s3, v[4:5]
	v_mad_u64_u32 v[64:65], s[76:77], v199, s3, v[4:5]
	v_mad_u64_u32 v[66:67], s[76:77], v198, s3, v[4:5]
	v_mad_u64_u32 v[68:69], s[76:77], v201, s3, v[4:5]
	v_mad_u64_u32 v[70:71], s[76:77], v200, s3, v[4:5]
	v_mad_u64_u32 v[72:73], s[76:77], v203, s3, v[4:5]
	v_mad_u64_u32 v[74:75], s[76:77], v202, s3, v[4:5]
	v_mad_u64_u32 v[76:77], s[76:77], v205, s3, v[4:5]
	v_mad_u64_u32 v[78:79], s[76:77], v204, s3, v[4:5]
	s_waitcnt vmcnt(15)
	ds_write_b32 v36, v206
	s_waitcnt vmcnt(14)
	ds_write_b32 v38, v212
	s_waitcnt vmcnt(13)
	ds_write_b32 v40, v213
	s_waitcnt vmcnt(12)
	ds_write_b32 v42, v214
	s_waitcnt vmcnt(11)
	ds_write_b32 v44, v207
	s_waitcnt vmcnt(10)
	ds_write_b32 v58, v208
	s_waitcnt vmcnt(9)
	ds_write_b32 v60, v215
	s_waitcnt vmcnt(8)
	ds_write_b32 v62, v216
	s_waitcnt vmcnt(7)
	ds_write_b32 v64, v209
	s_waitcnt vmcnt(6)
	ds_write_b32 v66, v210
	s_waitcnt vmcnt(5)
	ds_write_b32 v68, v217
	s_waitcnt vmcnt(4)
	ds_write_b32 v70, v218
	s_waitcnt vmcnt(3)
	ds_write_b32 v72, v189
	s_waitcnt vmcnt(2)
	ds_write_b32 v74, v211
	s_waitcnt vmcnt(1)
	ds_write_b32 v76, v219
	s_waitcnt vmcnt(0)
	ds_write_b32 v78, v221
	s_add_i32 s73, s73, 16
	s_add_i32 s2, s2, 16
	s_mov_b32 s74, 0
	s_cmp_lg_u32 s74, 0
	s_waitcnt lgkmcnt(0)
	ds_read2_b32 v[38:39], v50 offset0:33 offset1:41
	ds_read2_b32 v[40:41], v50 offset1:8
	ds_read2_b32 v[42:43], v50 offset0:66 offset1:74
	ds_read2_b32 v[44:45], v50 offset0:99 offset1:107
	ds_read2_b32 v[58:59], v50 offset0:132 offset1:140
	ds_read2_b32 v[60:61], v50 offset0:165 offset1:173
	ds_read2_b32 v[62:63], v50 offset0:198 offset1:206
	ds_read2_b32 v[64:65], v50 offset0:231 offset1:239
	v_or_b32_e32 v3, 0x80, v5
	v_lshlrev_b32_e32 v6, 1, v34
	v_or_b32_e32 v5, v3, v49
	v_lshl_add_u64 v[66:67], v[8:9], 0, v[6:7]
	v_lshlrev_b32_e32 v6, 12, v5
	s_waitcnt lgkmcnt(6)
	v_cvt_pk_bf16_f32 v34, v40, v38
	s_waitcnt lgkmcnt(4)
	v_cvt_pk_bf16_f32 v35, v42, v44
	s_waitcnt lgkmcnt(2)
	v_cvt_pk_bf16_f32 v36, v58, v60
	s_waitcnt lgkmcnt(0)
	v_cvt_pk_bf16_f32 v37, v62, v64
	v_lshl_add_u64 v[68:69], v[66:67], 0, v[6:7]
	global_store_dwordx4 v[68:69], v[34:37], off
	v_or_b32_e32 v5, v3, v51
	v_lshlrev_b32_e32 v6, 12, v5
	v_cvt_pk_bf16_f32 v34, v41, v39
	v_cvt_pk_bf16_f32 v35, v43, v45
	v_cvt_pk_bf16_f32 v36, v59, v61
	v_cvt_pk_bf16_f32 v37, v63, v65
	ds_read2_b32 v[40:41], v50 offset0:49 offset1:57
	ds_read2_b32 v[42:43], v50 offset0:16 offset1:24
	ds_read2_b32 v[44:45], v50 offset0:82 offset1:90
	ds_read2_b32 v[58:59], v50 offset0:115 offset1:123
	ds_read2_b32 v[60:61], v50 offset0:148 offset1:156
	ds_read2_b32 v[62:63], v50 offset0:181 offset1:189
	ds_read2_b32 v[64:65], v50 offset0:214 offset1:222
	ds_read2_b32 v[68:69], v50 offset0:247 offset1:255
	v_or_b32_e32 v5, v3, v52
	v_lshl_add_u64 v[38:39], v[66:67], 0, v[6:7]
	v_lshlrev_b32_e32 v6, 12, v5
	v_or_b32_e32 v3, v3, v53
	global_store_dwordx4 v[38:39], v[34:37], off
	v_lshl_add_u64 v[38:39], v[66:67], 0, v[6:7]
	v_lshlrev_b32_e32 v6, 12, v3
	s_waitcnt lgkmcnt(6)
	v_cvt_pk_bf16_f32 v34, v42, v40
	s_waitcnt lgkmcnt(4)
	v_cvt_pk_bf16_f32 v35, v44, v58
	s_waitcnt lgkmcnt(2)
	v_cvt_pk_bf16_f32 v36, v60, v62
	s_waitcnt lgkmcnt(0)
	v_cvt_pk_bf16_f32 v37, v64, v68
	global_store_dwordx4 v[38:39], v[34:37], off
	v_lshl_add_u64 v[38:39], v[66:67], 0, v[6:7]
	v_readlane_b32 s92, v252, 6
	v_cvt_pk_bf16_f32 v34, v43, v41
	v_cvt_pk_bf16_f32 v35, v45, v59
	v_cvt_pk_bf16_f32 v36, v61, v63
	v_cvt_pk_bf16_f32 v37, v65, v69
	global_store_dwordx4 v[38:39], v[34:37], off
	s_waitcnt lgkmcnt(0)
	v_readlane_b32 s93, v252, 7
	v_readlane_b32 s87, v252, 5

.LBB0_24:
	s_lshl_b32 s75, s2, 1
	s_lshl_b32 s76, s73, 1
	v_or_b32_e32 v158, s75, v1
	v_or_b32_e32 v159, s76, v2
	s_add_i32 s78, s76, 4
	s_add_i32 s77, s75, 4
	s_add_i32 s79, s75, 8
	s_add_i32 s80, s76, 8
	s_add_i32 s81, s75, 12
	s_add_i32 s83, s75, 16
	s_add_i32 s85, s75, 20
	s_add_i32 s87, s75, 24
	s_add_i32 s75, s75, 28
	v_add_lshl_u32 v6, v158, v3, 7
	v_add_lshl_u32 v38, v159, v34, 7
	v_or_b32_e32 v161, s78, v2
	s_add_i32 s82, s76, 12
	v_or_b32_e32 v160, s77, v1
	v_or_b32_e32 v162, s79, v1
	v_or_b32_e32 v163, s80, v2
	v_or_b32_e32 v164, s81, v1
	v_or_b32_e32 v166, s83, v1
	v_or_b32_e32 v168, s85, v1
	v_or_b32_e32 v170, s87, v1
	v_or_b32_e32 v172, s75, v1
	v_or_b32_e32 v36, v6, v35
	v_or_b32_e32 v6, v38, v35
	v_add_lshl_u32 v40, v161, v34, 7
	v_mov_b32_e32 v37, v7
	s_add_i32 s84, s76, 16
	v_or_b32_e32 v165, s82, v2
	v_add_lshl_u32 v38, v160, v3, 7
	v_add_lshl_u32 v42, v162, v3, 7
	v_add_lshl_u32 v84, v163, v34, 7
	v_add_lshl_u32 v44, v164, v3, 7
	v_add_lshl_u32 v58, v166, v3, 7
	v_add_lshl_u32 v60, v168, v3, 7
	v_add_lshl_u32 v62, v170, v3, 7
	v_add_lshl_u32 v66, v172, v3, 7
	v_lshl_add_u64 v[64:65], v[6:7], 2, s[22:23]
	v_or_b32_e32 v6, v40, v35
	v_mov_b32_e32 v39, v7
	s_add_i32 s86, s76, 20
	v_or_b32_e32 v167, s84, v2
	v_add_lshl_u32 v85, v165, v34, 7
	v_lshl_add_u64 v[36:37], v[36:37], 2, s[22:23]
	v_or_b32_e32 v38, v38, v35
	v_or_b32_e32 v40, v42, v35
	v_or_b32_e32 v42, v44, v35
	v_or_b32_e32 v44, v58, v35
	v_or_b32_e32 v58, v60, v35
	v_or_b32_e32 v60, v62, v35
	v_or_b32_e32 v62, v66, v35
	v_lshl_add_u64 v[66:67], v[6:7], 2, s[22:23]
	v_or_b32_e32 v6, v84, v35
	s_add_i32 s92, s76, 24
	v_or_b32_e32 v169, s86, v2
	v_add_lshl_u32 v86, v167, v34, 7
	v_lshl_add_u64 v[38:39], v[38:39], 2, s[22:23]
	global_load_dword v174, v[64:65], off
	global_load_dword v180, v[36:37], off
	global_load_dword v181, v[66:67], off
	global_load_dword v182, v[38:39], off
	v_lshl_add_u64 v[36:37], v[6:7], 2, s[22:23]
	v_or_b32_e32 v6, v85, v35
	v_mov_b32_e32 v41, v7
	v_mov_b32_e32 v43, v7
	s_add_i32 s76, s76, 28
	v_or_b32_e32 v171, s92, v2
	v_add_lshl_u32 v87, v169, v34, 7
	v_lshl_add_u64 v[38:39], v[6:7], 2, s[22:23]
	v_or_b32_e32 v6, v86, v35
	v_or_b32_e32 v173, s76, v2
	v_add_lshl_u32 v88, v171, v34, 7
	v_lshl_add_u64 v[40:41], v[40:41], 2, s[22:23]
	v_lshl_add_u64 v[42:43], v[42:43], 2, s[22:23]
	global_load_dword v175, v[36:37], off
	global_load_dword v176, v[40:41], off
	global_load_dword v183, v[38:39], off
	global_load_dword v184, v[42:43], off
	v_lshl_add_u64 v[36:37], v[6:7], 2, s[22:23]
	v_or_b32_e32 v6, v87, v35
	v_mov_b32_e32 v45, v7
	v_mov_b32_e32 v59, v7
	v_add_lshl_u32 v89, v173, v34, 7
	v_lshl_add_u64 v[38:39], v[6:7], 2, s[22:23]
	v_or_b32_e32 v6, v88, v35
	v_mov_b32_e32 v61, v7
	v_mov_b32_e32 v63, v7
	v_lshl_add_u64 v[44:45], v[44:45], 2, s[22:23]
	v_lshl_add_u64 v[58:59], v[58:59], 2, s[22:23]
	global_load_dword v177, v[36:37], off
	global_load_dword v178, v[44:45], off
	global_load_dword v185, v[38:39], off
	global_load_dword v186, v[58:59], off
	v_lshl_add_u64 v[36:37], v[6:7], 2, s[22:23]
	v_or_b32_e32 v6, v89, v35
	v_lshl_add_u64 v[60:61], v[60:61], 2, s[22:23]
	v_lshl_add_u64 v[62:63], v[62:63], 2, s[22:23]
	v_lshl_add_u64 v[38:39], v[6:7], 2, s[22:23]
	global_load_dword v157, v[36:37], off
	global_load_dword v179, v[60:61], off
	global_load_dword v187, v[38:39], off
	global_load_dword v188, v[62:63], off
	s_add_i32 s73, s73, 16
	s_add_i32 s2, s2, 16
	s_lshl_b32 s75, s2, 1
	s_lshl_b32 s76, s73, 1
	v_or_b32_e32 v190, s75, v1
	v_or_b32_e32 v191, s76, v2
	s_add_i32 s78, s76, 4
	s_add_i32 s77, s75, 4
	s_add_i32 s79, s75, 8
	s_add_i32 s80, s76, 8
	s_add_i32 s81, s75, 12
	s_add_i32 s83, s75, 16
	s_add_i32 s85, s75, 20
	s_add_i32 s87, s75, 24
	s_add_i32 s75, s75, 28
	v_add_lshl_u32 v6, v190, v3, 7
	v_add_lshl_u32 v38, v191, v34, 7
	v_or_b32_e32 v193, s78, v2
	s_add_i32 s82, s76, 12
	v_or_b32_e32 v192, s77, v1
	v_or_b32_e32 v194, s79, v1
	v_or_b32_e32 v195, s80, v2
	v_or_b32_e32 v196, s81, v1
	v_or_b32_e32 v198, s83, v1
	v_or_b32_e32 v200, s85, v1
	v_or_b32_e32 v202, s87, v1
	v_or_b32_e32 v204, s75, v1
	v_or_b32_e32 v36, v6, v35
	v_or_b32_e32 v6, v38, v35
	v_add_lshl_u32 v40, v193, v34, 7
	v_mov_b32_e32 v37, v7
	s_add_i32 s84, s76, 16
	v_or_b32_e32 v197, s82, v2
	v_add_lshl_u32 v38, v192, v3, 7
	v_add_lshl_u32 v42, v194, v3, 7
	v_add_lshl_u32 v84, v195, v34, 7
	v_add_lshl_u32 v44, v196, v3, 7
	v_add_lshl_u32 v58, v198, v3, 7
	v_add_lshl_u32 v60, v200, v3, 7
	v_add_lshl_u32 v62, v202, v3, 7
	v_add_lshl_u32 v66, v204, v3, 7
	v_lshl_add_u64 v[64:65], v[6:7], 2, s[22:23]
	v_or_b32_e32 v6, v40, v35
	v_mov_b32_e32 v39, v7
	s_add_i32 s86, s76, 20
	v_or_b32_e32 v199, s84, v2
	v_add_lshl_u32 v85, v197, v34, 7
	v_lshl_add_u64 v[36:37], v[36:37], 2, s[22:23]
	v_or_b32_e32 v38, v38, v35
	v_or_b32_e32 v40, v42, v35
	v_or_b32_e32 v42, v44, v35
	v_or_b32_e32 v44, v58, v35
	v_or_b32_e32 v58, v60, v35
	v_or_b32_e32 v60, v62, v35
	v_or_b32_e32 v62, v66, v35
	v_lshl_add_u64 v[66:67], v[6:7], 2, s[22:23]
	v_or_b32_e32 v6, v84, v35
	s_add_i32 s92, s76, 24
	v_or_b32_e32 v201, s86, v2
	v_add_lshl_u32 v86, v199, v34, 7
	v_lshl_add_u64 v[38:39], v[38:39], 2, s[22:23]
	global_load_dword v206, v[64:65], off
	global_load_dword v212, v[36:37], off
	global_load_dword v213, v[66:67], off
	global_load_dword v214, v[38:39], off
	v_lshl_add_u64 v[36:37], v[6:7], 2, s[22:23]
	v_or_b32_e32 v6, v85, v35
	v_mov_b32_e32 v41, v7
	v_mov_b32_e32 v43, v7
	s_add_i32 s76, s76, 28
	v_or_b32_e32 v203, s92, v2
	v_add_lshl_u32 v87, v201, v34, 7
	v_lshl_add_u64 v[38:39], v[6:7], 2, s[22:23]
	v_or_b32_e32 v6, v86, v35
	v_or_b32_e32 v205, s76, v2
	v_add_lshl_u32 v88, v203, v34, 7
	v_lshl_add_u64 v[40:41], v[40:41], 2, s[22:23]
	v_lshl_add_u64 v[42:43], v[42:43], 2, s[22:23]
	global_load_dword v207, v[36:37], off
	global_load_dword v208, v[40:41], off
	global_load_dword v215, v[38:39], off
	global_load_dword v216, v[42:43], off
	v_lshl_add_u64 v[36:37], v[6:7], 2, s[22:23]
	v_or_b32_e32 v6, v87, v35
	v_mov_b32_e32 v45, v7
	v_mov_b32_e32 v59, v7
	v_add_lshl_u32 v89, v205, v34, 7
	v_lshl_add_u64 v[38:39], v[6:7], 2, s[22:23]
	v_or_b32_e32 v6, v88, v35
	v_mov_b32_e32 v61, v7
	v_mov_b32_e32 v63, v7
	v_lshl_add_u64 v[44:45], v[44:45], 2, s[22:23]
	v_lshl_add_u64 v[58:59], v[58:59], 2, s[22:23]
	global_load_dword v209, v[36:37], off
	global_load_dword v210, v[44:45], off
	global_load_dword v217, v[38:39], off
	global_load_dword v218, v[58:59], off
	v_lshl_add_u64 v[36:37], v[6:7], 2, s[22:23]
	v_or_b32_e32 v6, v89, v35
	v_lshl_add_u64 v[60:61], v[60:61], 2, s[22:23]
	v_lshl_add_u64 v[62:63], v[62:63], 2, s[22:23]
	v_lshl_add_u64 v[38:39], v[6:7], 2, s[22:23]
	global_load_dword v189, v[36:37], off
	global_load_dword v211, v[60:61], off
	global_load_dword v219, v[38:39], off
	global_load_dword v221, v[62:63], off
	v_mad_u64_u32 v[36:37], s[76:77], v159, s3, v[4:5]
	v_mad_u64_u32 v[38:39], s[76:77], v158, s3, v[4:5]
	v_mad_u64_u32 v[40:41], s[76:77], v161, s3, v[4:5]
	v_mad_u64_u32 v[42:43], s[76:77], v160, s3, v[4:5]
	v_mad_u64_u32 v[44:45], s[76:77], v163, s3, v[4:5]
	v_mad_u64_u32 v[58:59], s[76:77], v162, s3, v[4:5]
	v_mad_u64_u32 v[60:61], s[76:77], v165, s3, v[4:5]
	v_mad_u64_u32 v[62:63], s[76:77], v164, s3, v[4:5]
	v_mad_u64_u32 v[64:65], s[76:77], v167, s3, v[4:5]
	v_mad_u64_u32 v[66:67], s[76:77], v166, s3, v[4:5]
	v_mad_u64_u32 v[68:69], s[76:77], v169, s3, v[4:5]
	v_mad_u64_u32 v[70:71], s[76:77], v168, s3, v[4:5]
	v_mad_u64_u32 v[72:73], s[76:77], v171, s3, v[4:5]
	v_mad_u64_u32 v[74:75], s[76:77], v170, s3, v[4:5]
	v_mad_u64_u32 v[76:77], s[76:77], v173, s3, v[4:5]
	v_mad_u64_u32 v[78:79], s[76:77], v172, s3, v[4:5]
	s_waitcnt vmcnt(31)
	ds_write_b32 v36, v174
	s_waitcnt vmcnt(30)
	ds_write_b32 v38, v180
	s_waitcnt vmcnt(29)
	ds_write_b32 v40, v181
	s_waitcnt vmcnt(28)
	ds_write_b32 v42, v182
	s_waitcnt vmcnt(27)
	ds_write_b32 v44, v175
	s_waitcnt vmcnt(26)
	ds_write_b32 v58, v176
	s_waitcnt vmcnt(25)
	ds_write_b32 v60, v183
	s_waitcnt vmcnt(24)
	ds_write_b32 v62, v184
	s_waitcnt vmcnt(23)
	ds_write_b32 v64, v177
	s_waitcnt vmcnt(22)
	ds_write_b32 v66, v178
	s_waitcnt vmcnt(21)
	ds_write_b32 v68, v185
	s_waitcnt vmcnt(20)
	ds_write_b32 v70, v186
	s_waitcnt vmcnt(19)
	ds_write_b32 v72, v157
	s_waitcnt vmcnt(18)
	ds_write_b32 v74, v179
	s_waitcnt vmcnt(17)
	ds_write_b32 v76, v187
	s_waitcnt vmcnt(16)
	ds_write_b32 v78, v188
	v_mad_u64_u32 v[36:37], s[76:77], v191, s3, v[4:5]
	v_mad_u64_u32 v[38:39], s[76:77], v190, s3, v[4:5]
	v_mad_u64_u32 v[40:41], s[76:77], v193, s3, v[4:5]
	v_mad_u64_u32 v[42:43], s[76:77], v192, s3, v[4:5]
	v_mad_u64_u32 v[44:45], s[76:77], v195, s3, v[4:5]
	v_mad_u64_u32 v[58:59], s[76:77], v194, s3, v[4:5]
	v_mad_u64_u32 v[60:61], s[76:77], v197, s3, v[4:5]
	v_mad_u64_u32 v[62:63], s[76:77], v196, s3, v[4:5]
	v_mad_u64_u32 v[64:65], s[76:77], v199, s3, v[4:5]
	v_mad_u64_u32 v[66:67], s[76:77], v198, s3, v[4:5]
	v_mad_u64_u32 v[68:69], s[76:77], v201, s3, v[4:5]
	v_mad_u64_u32 v[70:71], s[76:77], v200, s3, v[4:5]
	v_mad_u64_u32 v[72:73], s[76:77], v203, s3, v[4:5]
	v_mad_u64_u32 v[74:75], s[76:77], v202, s3, v[4:5]
	v_mad_u64_u32 v[76:77], s[76:77], v205, s3, v[4:5]
	v_mad_u64_u32 v[78:79], s[76:77], v204, s3, v[4:5]
	s_waitcnt vmcnt(15)
	ds_write_b32 v36, v206
	s_waitcnt vmcnt(14)
	ds_write_b32 v38, v212
	s_waitcnt vmcnt(13)
	ds_write_b32 v40, v213
	s_waitcnt vmcnt(12)
	ds_write_b32 v42, v214
	s_waitcnt vmcnt(11)
	ds_write_b32 v44, v207
	s_waitcnt vmcnt(10)
	ds_write_b32 v58, v208
	s_waitcnt vmcnt(9)
	ds_write_b32 v60, v215
	s_waitcnt vmcnt(8)
	ds_write_b32 v62, v216
	s_waitcnt vmcnt(7)
	ds_write_b32 v64, v209
	s_waitcnt vmcnt(6)
	ds_write_b32 v66, v210
	s_waitcnt vmcnt(5)
	ds_write_b32 v68, v217
	s_waitcnt vmcnt(4)
	ds_write_b32 v70, v218
	s_waitcnt vmcnt(3)
	ds_write_b32 v72, v189
	s_waitcnt vmcnt(2)
	ds_write_b32 v74, v211
	s_waitcnt vmcnt(1)
	ds_write_b32 v76, v219
	s_waitcnt vmcnt(0)
	ds_write_b32 v78, v221
	s_add_i32 s73, s73, 16
	s_add_i32 s2, s2, 16
	s_mov_b32 s74, 0
	s_cmp_lg_u32 s74, 0
	s_waitcnt lgkmcnt(0)
	ds_read2_b32 v[38:39], v50 offset0:33 offset1:41
	ds_read2_b32 v[40:41], v50 offset1:8
	ds_read2_b32 v[42:43], v50 offset0:66 offset1:74
	ds_read2_b32 v[44:45], v50 offset0:99 offset1:107
	ds_read2_b32 v[58:59], v50 offset0:132 offset1:140
	ds_read2_b32 v[60:61], v50 offset0:165 offset1:173
	ds_read2_b32 v[62:63], v50 offset0:198 offset1:206
	ds_read2_b32 v[64:65], v50 offset0:231 offset1:239
	v_lshlrev_b32_e32 v6, 1, v34
	v_or_b32_e32 v3, v5, v49
	v_lshl_add_u64 v[66:67], v[8:9], 0, v[6:7]
	v_lshlrev_b32_e32 v6, 12, v3
	s_waitcnt lgkmcnt(6)
	v_cvt_pk_bf16_f32 v34, v40, v38
	s_waitcnt lgkmcnt(4)
	v_cvt_pk_bf16_f32 v35, v42, v44
	s_waitcnt lgkmcnt(2)
	v_cvt_pk_bf16_f32 v36, v58, v60
	s_waitcnt lgkmcnt(0)
	v_cvt_pk_bf16_f32 v37, v62, v64
	v_lshl_add_u64 v[68:69], v[66:67], 0, v[6:7]
	global_store_dwordx4 v[68:69], v[34:37], off
	v_or_b32_e32 v3, v5, v51
	v_lshlrev_b32_e32 v6, 12, v3
	v_cvt_pk_bf16_f32 v34, v41, v39
	v_cvt_pk_bf16_f32 v35, v43, v45
	v_cvt_pk_bf16_f32 v36, v59, v61
	v_cvt_pk_bf16_f32 v37, v63, v65
	ds_read2_b32 v[40:41], v50 offset0:49 offset1:57
	ds_read2_b32 v[42:43], v50 offset0:16 offset1:24
	ds_read2_b32 v[44:45], v50 offset0:82 offset1:90
	ds_read2_b32 v[58:59], v50 offset0:115 offset1:123
	ds_read2_b32 v[60:61], v50 offset0:148 offset1:156
	ds_read2_b32 v[62:63], v50 offset0:181 offset1:189
	ds_read2_b32 v[64:65], v50 offset0:214 offset1:222
	ds_read2_b32 v[68:69], v50 offset0:247 offset1:255
	v_or_b32_e32 v3, v5, v52
	v_lshl_add_u64 v[38:39], v[66:67], 0, v[6:7]
	v_lshlrev_b32_e32 v6, 12, v3
	v_or_b32_e32 v3, v5, v53
	global_store_dwordx4 v[38:39], v[34:37], off
	v_lshl_add_u64 v[38:39], v[66:67], 0, v[6:7]
	v_lshlrev_b32_e32 v6, 12, v3
	s_waitcnt lgkmcnt(6)
	v_cvt_pk_bf16_f32 v34, v42, v40
	s_waitcnt lgkmcnt(4)
	v_cvt_pk_bf16_f32 v35, v44, v58
	s_waitcnt lgkmcnt(2)
	v_cvt_pk_bf16_f32 v36, v60, v62
	s_waitcnt lgkmcnt(0)
	v_cvt_pk_bf16_f32 v37, v64, v68
	global_store_dwordx4 v[38:39], v[34:37], off
	v_lshl_add_u64 v[38:39], v[66:67], 0, v[6:7]
	v_readlane_b32 s92, v252, 6
	v_cvt_pk_bf16_f32 v34, v43, v41
	v_cvt_pk_bf16_f32 v35, v45, v59
	v_cvt_pk_bf16_f32 v36, v61, v63
	v_cvt_pk_bf16_f32 v37, v65, v69
	global_store_dwordx4 v[38:39], v[34:37], off
	s_waitcnt lgkmcnt(0)
	v_readlane_b32 s93, v252, 7
	v_readlane_b32 s87, v252, 5

.LBB0_29:
	s_lshl_b32 s73, s2, 1
	s_lshl_b32 s74, s50, 1
	v_or_b32_e32 v158, s73, v1
	v_or_b32_e32 v159, s74, v2
	s_add_i32 s76, s74, 4
	s_add_i32 s75, s73, 4
	s_add_i32 s77, s73, 8
	s_add_i32 s78, s74, 8
	s_add_i32 s79, s73, 12
	s_add_i32 s81, s73, 16
	s_add_i32 s83, s73, 20
	s_add_i32 s85, s73, 24
	s_add_i32 s73, s73, 28
	v_add_lshl_u32 v6, v158, v3, 10
	v_add_lshl_u32 v40, v159, v34, 10
	v_or_b32_e32 v161, s76, v2
	s_add_i32 s80, s74, 12
	v_or_b32_e32 v160, s75, v1
	v_or_b32_e32 v162, s77, v1
	v_or_b32_e32 v163, s78, v2
	v_or_b32_e32 v164, s79, v1
	v_or_b32_e32 v166, s81, v1
	v_or_b32_e32 v168, s83, v1
	v_or_b32_e32 v170, s85, v1
	v_or_b32_e32 v172, s73, v1
	v_or_b32_e32 v38, v5, v6
	v_or_b32_e32 v6, v36, v40
	v_add_lshl_u32 v42, v161, v34, 10
	v_mov_b32_e32 v39, v7
	s_add_i32 s82, s74, 16
	v_or_b32_e32 v165, s80, v2
	v_add_lshl_u32 v40, v160, v3, 10
	v_add_lshl_u32 v44, v162, v3, 10
	v_add_lshl_u32 v85, v163, v34, 10
	v_add_lshl_u32 v58, v164, v3, 10
	v_add_lshl_u32 v60, v166, v3, 10
	v_add_lshl_u32 v62, v168, v3, 10
	v_add_lshl_u32 v64, v170, v3, 10
	v_add_lshl_u32 v68, v172, v3, 10
	v_lshl_add_u64 v[66:67], v[6:7], 2, s[24:25]
	v_or_b32_e32 v6, v36, v42
	v_mov_b32_e32 v41, v7
	s_add_i32 s84, s74, 20
	v_or_b32_e32 v167, s82, v2
	v_add_lshl_u32 v86, v165, v34, 10
	v_lshl_add_u64 v[38:39], v[38:39], 2, s[24:25]
	v_or_b32_e32 v40, v5, v40
	v_or_b32_e32 v42, v5, v44
	v_or_b32_e32 v44, v5, v58
	v_or_b32_e32 v58, v5, v60
	v_or_b32_e32 v60, v5, v62
	v_or_b32_e32 v62, v5, v64
	v_or_b32_e32 v64, v5, v68
	v_lshl_add_u64 v[68:69], v[6:7], 2, s[24:25]
	v_or_b32_e32 v6, v36, v85
	s_add_i32 s86, s74, 24
	v_or_b32_e32 v169, s84, v2
	v_add_lshl_u32 v87, v167, v34, 10
	v_lshl_add_u64 v[40:41], v[40:41], 2, s[24:25]
	global_load_dword v174, v[66:67], off
	global_load_dword v180, v[38:39], off
	global_load_dword v181, v[68:69], off
	global_load_dword v182, v[40:41], off
	v_lshl_add_u64 v[38:39], v[6:7], 2, s[24:25]
	v_or_b32_e32 v6, v36, v86
	v_mov_b32_e32 v43, v7
	v_mov_b32_e32 v45, v7
	s_add_i32 s74, s74, 28
	v_or_b32_e32 v171, s86, v2
	v_add_lshl_u32 v88, v169, v34, 10
	v_lshl_add_u64 v[40:41], v[6:7], 2, s[24:25]
	v_or_b32_e32 v6, v36, v87
	v_or_b32_e32 v173, s74, v2
	v_add_lshl_u32 v89, v171, v34, 10
	v_lshl_add_u64 v[42:43], v[42:43], 2, s[24:25]
	v_lshl_add_u64 v[44:45], v[44:45], 2, s[24:25]
	global_load_dword v175, v[38:39], off
	global_load_dword v176, v[42:43], off
	global_load_dword v183, v[40:41], off
	global_load_dword v184, v[44:45], off
	v_lshl_add_u64 v[38:39], v[6:7], 2, s[24:25]
	v_or_b32_e32 v6, v36, v88
	v_mov_b32_e32 v59, v7
	v_mov_b32_e32 v61, v7
	v_add_lshl_u32 v90, v173, v34, 10
	v_lshl_add_u64 v[40:41], v[6:7], 2, s[24:25]
	v_or_b32_e32 v6, v36, v89
	v_mov_b32_e32 v63, v7
	v_mov_b32_e32 v65, v7
	v_lshl_add_u64 v[58:59], v[58:59], 2, s[24:25]
	v_lshl_add_u64 v[60:61], v[60:61], 2, s[24:25]
	global_load_dword v177, v[38:39], off
	global_load_dword v178, v[58:59], off
	global_load_dword v185, v[40:41], off
	global_load_dword v186, v[60:61], off
	v_lshl_add_u64 v[38:39], v[6:7], 2, s[24:25]
	v_or_b32_e32 v6, v36, v90
	v_lshl_add_u64 v[62:63], v[62:63], 2, s[24:25]
	v_lshl_add_u64 v[64:65], v[64:65], 2, s[24:25]
	v_lshl_add_u64 v[40:41], v[6:7], 2, s[24:25]
	global_load_dword v157, v[38:39], off
	global_load_dword v179, v[62:63], off
	global_load_dword v187, v[40:41], off
	global_load_dword v188, v[64:65], off
	s_add_i32 s50, s50, 16
	s_add_i32 s2, s2, 16
	s_lshl_b32 s73, s2, 1
	s_lshl_b32 s74, s50, 1
	v_or_b32_e32 v190, s73, v1
	v_or_b32_e32 v191, s74, v2
	s_add_i32 s76, s74, 4
	s_add_i32 s75, s73, 4
	s_add_i32 s77, s73, 8
	s_add_i32 s78, s74, 8
	s_add_i32 s79, s73, 12
	s_add_i32 s81, s73, 16
	s_add_i32 s83, s73, 20
	s_add_i32 s85, s73, 24
	s_add_i32 s73, s73, 28
	v_add_lshl_u32 v6, v190, v3, 10
	v_add_lshl_u32 v40, v191, v34, 10
	v_or_b32_e32 v193, s76, v2
	s_add_i32 s80, s74, 12
	v_or_b32_e32 v192, s75, v1
	v_or_b32_e32 v194, s77, v1
	v_or_b32_e32 v195, s78, v2
	v_or_b32_e32 v196, s79, v1
	v_or_b32_e32 v198, s81, v1
	v_or_b32_e32 v200, s83, v1
	v_or_b32_e32 v202, s85, v1
	v_or_b32_e32 v204, s73, v1
	v_or_b32_e32 v38, v5, v6
	v_or_b32_e32 v6, v36, v40
	v_add_lshl_u32 v42, v193, v34, 10
	v_mov_b32_e32 v39, v7
	s_add_i32 s82, s74, 16
	v_or_b32_e32 v197, s80, v2
	v_add_lshl_u32 v40, v192, v3, 10
	v_add_lshl_u32 v44, v194, v3, 10
	v_add_lshl_u32 v85, v195, v34, 10
	v_add_lshl_u32 v58, v196, v3, 10
	v_add_lshl_u32 v60, v198, v3, 10
	v_add_lshl_u32 v62, v200, v3, 10
	v_add_lshl_u32 v64, v202, v3, 10
	v_add_lshl_u32 v68, v204, v3, 10
	v_lshl_add_u64 v[66:67], v[6:7], 2, s[24:25]
	v_or_b32_e32 v6, v36, v42
	v_mov_b32_e32 v41, v7
	s_add_i32 s84, s74, 20
	v_or_b32_e32 v199, s82, v2
	v_add_lshl_u32 v86, v197, v34, 10
	v_lshl_add_u64 v[38:39], v[38:39], 2, s[24:25]
	v_or_b32_e32 v40, v5, v40
	v_or_b32_e32 v42, v5, v44
	v_or_b32_e32 v44, v5, v58
	v_or_b32_e32 v58, v5, v60
	v_or_b32_e32 v60, v5, v62
	v_or_b32_e32 v62, v5, v64
	v_or_b32_e32 v64, v5, v68
	v_lshl_add_u64 v[68:69], v[6:7], 2, s[24:25]
	v_or_b32_e32 v6, v36, v85
	s_add_i32 s86, s74, 24
	v_or_b32_e32 v201, s84, v2
	v_add_lshl_u32 v87, v199, v34, 10
	v_lshl_add_u64 v[40:41], v[40:41], 2, s[24:25]
	global_load_dword v206, v[66:67], off
	global_load_dword v212, v[38:39], off
	global_load_dword v213, v[68:69], off
	global_load_dword v214, v[40:41], off
	v_lshl_add_u64 v[38:39], v[6:7], 2, s[24:25]
	v_or_b32_e32 v6, v36, v86
	v_mov_b32_e32 v43, v7
	v_mov_b32_e32 v45, v7
	s_add_i32 s74, s74, 28
	v_or_b32_e32 v203, s86, v2
	v_add_lshl_u32 v88, v201, v34, 10
	v_lshl_add_u64 v[40:41], v[6:7], 2, s[24:25]
	v_or_b32_e32 v6, v36, v87
	v_or_b32_e32 v205, s74, v2
	v_add_lshl_u32 v89, v203, v34, 10
	v_lshl_add_u64 v[42:43], v[42:43], 2, s[24:25]
	v_lshl_add_u64 v[44:45], v[44:45], 2, s[24:25]
	global_load_dword v207, v[38:39], off
	global_load_dword v208, v[42:43], off
	global_load_dword v215, v[40:41], off
	global_load_dword v216, v[44:45], off
	v_lshl_add_u64 v[38:39], v[6:7], 2, s[24:25]
	v_or_b32_e32 v6, v36, v88
	v_mov_b32_e32 v59, v7
	v_mov_b32_e32 v61, v7
	v_add_lshl_u32 v90, v205, v34, 10
	v_lshl_add_u64 v[40:41], v[6:7], 2, s[24:25]
	v_or_b32_e32 v6, v36, v89
	v_mov_b32_e32 v63, v7
	v_mov_b32_e32 v65, v7
	v_lshl_add_u64 v[58:59], v[58:59], 2, s[24:25]
	v_lshl_add_u64 v[60:61], v[60:61], 2, s[24:25]
	global_load_dword v209, v[38:39], off
	global_load_dword v210, v[58:59], off
	global_load_dword v217, v[40:41], off
	global_load_dword v218, v[60:61], off
	v_lshl_add_u64 v[38:39], v[6:7], 2, s[24:25]
	v_or_b32_e32 v6, v36, v90
	v_lshl_add_u64 v[62:63], v[62:63], 2, s[24:25]
	v_lshl_add_u64 v[64:65], v[64:65], 2, s[24:25]
	v_lshl_add_u64 v[40:41], v[6:7], 2, s[24:25]
	global_load_dword v189, v[38:39], off
	global_load_dword v211, v[62:63], off
	global_load_dword v219, v[40:41], off
	global_load_dword v221, v[64:65], off
	v_mad_u64_u32 v[38:39], s[74:75], v159, s3, v[4:5]
	v_mad_u64_u32 v[40:41], s[74:75], v158, s3, v[4:5]
	v_mad_u64_u32 v[42:43], s[74:75], v161, s3, v[4:5]
	v_mad_u64_u32 v[44:45], s[74:75], v160, s3, v[4:5]
	v_mad_u64_u32 v[58:59], s[74:75], v163, s3, v[4:5]
	v_mad_u64_u32 v[60:61], s[74:75], v162, s3, v[4:5]
	v_mad_u64_u32 v[62:63], s[74:75], v165, s3, v[4:5]
	v_mad_u64_u32 v[64:65], s[74:75], v164, s3, v[4:5]
	v_mad_u64_u32 v[66:67], s[74:75], v167, s3, v[4:5]
	v_mad_u64_u32 v[68:69], s[74:75], v166, s3, v[4:5]
	v_mad_u64_u32 v[70:71], s[74:75], v169, s3, v[4:5]
	v_mad_u64_u32 v[72:73], s[74:75], v168, s3, v[4:5]
	v_mad_u64_u32 v[74:75], s[74:75], v171, s3, v[4:5]
	v_mad_u64_u32 v[76:77], s[74:75], v170, s3, v[4:5]
	v_mad_u64_u32 v[78:79], s[74:75], v173, s3, v[4:5]
	v_mad_u64_u32 v[80:81], s[74:75], v172, s3, v[4:5]
	s_waitcnt vmcnt(31)
	ds_write_b32 v38, v174
	s_waitcnt vmcnt(30)
	ds_write_b32 v40, v180
	s_waitcnt vmcnt(29)
	ds_write_b32 v42, v181
	s_waitcnt vmcnt(28)
	ds_write_b32 v44, v182
	s_waitcnt vmcnt(27)
	ds_write_b32 v58, v175
	s_waitcnt vmcnt(26)
	ds_write_b32 v60, v176
	s_waitcnt vmcnt(25)
	ds_write_b32 v62, v183
	s_waitcnt vmcnt(24)
	ds_write_b32 v64, v184
	s_waitcnt vmcnt(23)
	ds_write_b32 v66, v177
	s_waitcnt vmcnt(22)
	ds_write_b32 v68, v178
	s_waitcnt vmcnt(21)
	ds_write_b32 v70, v185
	s_waitcnt vmcnt(20)
	ds_write_b32 v72, v186
	s_waitcnt vmcnt(19)
	ds_write_b32 v74, v157
	s_waitcnt vmcnt(18)
	ds_write_b32 v76, v179
	s_waitcnt vmcnt(17)
	ds_write_b32 v78, v187
	s_waitcnt vmcnt(16)
	ds_write_b32 v80, v188
	v_mad_u64_u32 v[38:39], s[74:75], v191, s3, v[4:5]
	v_mad_u64_u32 v[40:41], s[74:75], v190, s3, v[4:5]
	v_mad_u64_u32 v[42:43], s[74:75], v193, s3, v[4:5]
	v_mad_u64_u32 v[44:45], s[74:75], v192, s3, v[4:5]
	v_mad_u64_u32 v[58:59], s[74:75], v195, s3, v[4:5]
	v_mad_u64_u32 v[60:61], s[74:75], v194, s3, v[4:5]
	v_mad_u64_u32 v[62:63], s[74:75], v197, s3, v[4:5]
	v_mad_u64_u32 v[64:65], s[74:75], v196, s3, v[4:5]
	v_mad_u64_u32 v[66:67], s[74:75], v199, s3, v[4:5]
	v_mad_u64_u32 v[68:69], s[74:75], v198, s3, v[4:5]
	v_mad_u64_u32 v[70:71], s[74:75], v201, s3, v[4:5]
	v_mad_u64_u32 v[72:73], s[74:75], v200, s3, v[4:5]
	v_mad_u64_u32 v[74:75], s[74:75], v203, s3, v[4:5]
	v_mad_u64_u32 v[76:77], s[74:75], v202, s3, v[4:5]
	v_mad_u64_u32 v[78:79], s[74:75], v205, s3, v[4:5]
	v_mad_u64_u32 v[80:81], s[74:75], v204, s3, v[4:5]
	s_waitcnt vmcnt(15)
	ds_write_b32 v38, v206
	s_waitcnt vmcnt(14)
	ds_write_b32 v40, v212
	s_waitcnt vmcnt(13)
	ds_write_b32 v42, v213
	s_waitcnt vmcnt(12)
	ds_write_b32 v44, v214
	s_waitcnt vmcnt(11)
	ds_write_b32 v58, v207
	s_waitcnt vmcnt(10)
	ds_write_b32 v60, v208
	s_waitcnt vmcnt(9)
	ds_write_b32 v62, v215
	s_waitcnt vmcnt(8)
	ds_write_b32 v64, v216
	s_waitcnt vmcnt(7)
	ds_write_b32 v66, v209
	s_waitcnt vmcnt(6)
	ds_write_b32 v68, v210
	s_waitcnt vmcnt(5)
	ds_write_b32 v70, v217
	s_waitcnt vmcnt(4)
	ds_write_b32 v72, v218
	s_waitcnt vmcnt(3)
	ds_write_b32 v74, v189
	s_waitcnt vmcnt(2)
	ds_write_b32 v76, v211
	s_waitcnt vmcnt(1)
	ds_write_b32 v78, v219
	s_waitcnt vmcnt(0)
	ds_write_b32 v80, v221
	s_add_i32 s50, s50, 16
	s_add_i32 s2, s2, 16
	s_mov_b32 s51, 0
	s_cmp_lg_u32 s51, 0
	s_waitcnt lgkmcnt(0)
	ds_read2_b32 v[40:41], v50 offset0:33 offset1:41
	ds_read2_b32 v[42:43], v50 offset1:8
	ds_read2_b32 v[44:45], v50 offset0:66 offset1:74
	ds_read2_b32 v[58:59], v50 offset0:99 offset1:107
	ds_read2_b32 v[60:61], v50 offset0:132 offset1:140
	ds_read2_b32 v[62:63], v50 offset0:165 offset1:173
	ds_read2_b32 v[64:65], v50 offset0:198 offset1:206
	ds_read2_b32 v[66:67], v50 offset0:231 offset1:239
	v_lshlrev_b32_e32 v6, 1, v34
	v_or_b32_sdwa v3, v49, v35 dst_sel:DWORD dst_unused:UNUSED_PAD src0_sel:DWORD src1_sel:WORD_0
	v_lshl_add_u64 v[68:69], v[10:11], 0, v[6:7]
	v_lshlrev_b32_e32 v6, 11, v3
	s_waitcnt lgkmcnt(6)
	v_cvt_pk_bf16_f32 v36, v42, v40
	s_waitcnt lgkmcnt(4)
	v_cvt_pk_bf16_f32 v37, v44, v58
	s_waitcnt lgkmcnt(2)
	v_cvt_pk_bf16_f32 v38, v60, v62
	s_waitcnt lgkmcnt(0)
	v_cvt_pk_bf16_f32 v39, v64, v66
	v_lshl_add_u64 v[70:71], v[68:69], 0, v[6:7]
	global_store_dwordx4 v[70:71], v[36:39], off
	v_or_b32_sdwa v3, v51, v35 dst_sel:DWORD dst_unused:UNUSED_PAD src0_sel:DWORD src1_sel:WORD_0
	v_lshlrev_b32_e32 v6, 11, v3
	v_cvt_pk_bf16_f32 v36, v43, v41
	v_cvt_pk_bf16_f32 v37, v45, v59
	v_cvt_pk_bf16_f32 v38, v61, v63
	v_cvt_pk_bf16_f32 v39, v65, v67
	ds_read2_b32 v[42:43], v50 offset0:49 offset1:57
	ds_read2_b32 v[44:45], v50 offset0:16 offset1:24
	ds_read2_b32 v[58:59], v50 offset0:82 offset1:90
	ds_read2_b32 v[60:61], v50 offset0:115 offset1:123
	ds_read2_b32 v[62:63], v50 offset0:148 offset1:156
	ds_read2_b32 v[64:65], v50 offset0:181 offset1:189
	ds_read2_b32 v[66:67], v50 offset0:214 offset1:222
	ds_read2_b32 v[70:71], v50 offset0:247 offset1:255
	v_or_b32_sdwa v3, v52, v35 dst_sel:DWORD dst_unused:UNUSED_PAD src0_sel:DWORD src1_sel:WORD_0
	v_lshl_add_u64 v[40:41], v[68:69], 0, v[6:7]
	v_lshlrev_b32_e32 v6, 11, v3
	v_or_b32_sdwa v3, v53, v35 dst_sel:DWORD dst_unused:UNUSED_PAD src0_sel:DWORD src1_sel:WORD_0
	global_store_dwordx4 v[40:41], v[36:39], off
	v_lshl_add_u64 v[40:41], v[68:69], 0, v[6:7]
	v_lshlrev_b32_e32 v6, 11, v3
	s_waitcnt lgkmcnt(6)
	v_cvt_pk_bf16_f32 v36, v44, v42
	s_waitcnt lgkmcnt(4)
	v_cvt_pk_bf16_f32 v37, v58, v60
	s_waitcnt lgkmcnt(2)
	v_cvt_pk_bf16_f32 v38, v62, v64
	s_waitcnt lgkmcnt(0)
	v_cvt_pk_bf16_f32 v39, v66, v70
	global_store_dwordx4 v[40:41], v[36:39], off
	v_lshl_add_u64 v[34:35], v[68:69], 0, v[6:7]
	s_nop 0
	v_cvt_pk_bf16_f32 v36, v45, v43
	v_cvt_pk_bf16_f32 v37, v59, v61
	v_cvt_pk_bf16_f32 v38, v63, v65
	v_cvt_pk_bf16_f32 v39, v67, v71
	global_store_dwordx4 v[34:35], v[36:39], off
	s_waitcnt lgkmcnt(0)

.LBB0_34:
	s_lshl_b32 s50, s2, 1
	s_lshl_b32 s51, s48, 1
	v_or_b32_e32 v158, s50, v1
	v_or_b32_e32 v159, s51, v2
	s_add_i32 s74, s51, 4
	s_add_i32 s73, s50, 4
	s_add_i32 s75, s50, 8
	s_add_i32 s76, s51, 8
	s_add_i32 s77, s50, 12
	s_add_i32 s79, s50, 16
	s_add_i32 s81, s50, 20
	s_add_i32 s83, s50, 24
	s_add_i32 s50, s50, 28
	v_add_lshl_u32 v6, v158, v3, 10
	v_add_lshl_u32 v40, v159, v34, 10
	v_or_b32_e32 v161, s74, v2
	s_add_i32 s78, s51, 12
	v_or_b32_e32 v160, s73, v1
	v_or_b32_e32 v162, s75, v1
	v_or_b32_e32 v163, s76, v2
	v_or_b32_e32 v164, s77, v1
	v_or_b32_e32 v166, s79, v1
	v_or_b32_e32 v168, s81, v1
	v_or_b32_e32 v170, s83, v1
	v_or_b32_e32 v172, s50, v1
	v_or_b32_e32 v38, v5, v6
	v_or_b32_e32 v6, v36, v40
	v_add_lshl_u32 v42, v161, v34, 10
	v_mov_b32_e32 v39, v7
	s_add_i32 s80, s51, 16
	v_or_b32_e32 v165, s78, v2
	v_add_lshl_u32 v40, v160, v3, 10
	v_add_lshl_u32 v44, v162, v3, 10
	v_add_lshl_u32 v85, v163, v34, 10
	v_add_lshl_u32 v58, v164, v3, 10
	v_add_lshl_u32 v60, v166, v3, 10
	v_add_lshl_u32 v62, v168, v3, 10
	v_add_lshl_u32 v64, v170, v3, 10
	v_add_lshl_u32 v68, v172, v3, 10
	v_lshl_add_u64 v[66:67], v[6:7], 2, s[10:11]
	v_or_b32_e32 v6, v36, v42
	v_mov_b32_e32 v41, v7
	s_add_i32 s82, s51, 20
	v_or_b32_e32 v167, s80, v2
	v_add_lshl_u32 v86, v165, v34, 10
	v_lshl_add_u64 v[38:39], v[38:39], 2, s[10:11]
	v_or_b32_e32 v40, v5, v40
	v_or_b32_e32 v42, v5, v44
	v_or_b32_e32 v44, v5, v58
	v_or_b32_e32 v58, v5, v60
	v_or_b32_e32 v60, v5, v62
	v_or_b32_e32 v62, v5, v64
	v_or_b32_e32 v64, v5, v68
	v_lshl_add_u64 v[68:69], v[6:7], 2, s[10:11]
	v_or_b32_e32 v6, v36, v85
	s_add_i32 s84, s51, 24
	v_or_b32_e32 v169, s82, v2
	v_add_lshl_u32 v87, v167, v34, 10
	v_lshl_add_u64 v[40:41], v[40:41], 2, s[10:11]
	global_load_dword v174, v[66:67], off
	global_load_dword v180, v[38:39], off
	global_load_dword v181, v[68:69], off
	global_load_dword v182, v[40:41], off
	v_lshl_add_u64 v[38:39], v[6:7], 2, s[10:11]
	v_or_b32_e32 v6, v36, v86
	v_mov_b32_e32 v43, v7
	v_mov_b32_e32 v45, v7
	s_add_i32 s51, s51, 28
	v_or_b32_e32 v171, s84, v2
	v_add_lshl_u32 v88, v169, v34, 10
	v_lshl_add_u64 v[40:41], v[6:7], 2, s[10:11]
	v_or_b32_e32 v6, v36, v87
	v_or_b32_e32 v173, s51, v2
	v_add_lshl_u32 v89, v171, v34, 10
	v_lshl_add_u64 v[42:43], v[42:43], 2, s[10:11]
	v_lshl_add_u64 v[44:45], v[44:45], 2, s[10:11]
	global_load_dword v175, v[38:39], off
	global_load_dword v176, v[42:43], off
	global_load_dword v183, v[40:41], off
	global_load_dword v184, v[44:45], off
	v_lshl_add_u64 v[38:39], v[6:7], 2, s[10:11]
	v_or_b32_e32 v6, v36, v88
	v_mov_b32_e32 v59, v7
	v_mov_b32_e32 v61, v7
	v_add_lshl_u32 v90, v173, v34, 10
	v_lshl_add_u64 v[40:41], v[6:7], 2, s[10:11]
	v_or_b32_e32 v6, v36, v89
	v_mov_b32_e32 v63, v7
	v_mov_b32_e32 v65, v7
	v_lshl_add_u64 v[58:59], v[58:59], 2, s[10:11]
	v_lshl_add_u64 v[60:61], v[60:61], 2, s[10:11]
	global_load_dword v177, v[38:39], off
	global_load_dword v178, v[58:59], off
	global_load_dword v185, v[40:41], off
	global_load_dword v186, v[60:61], off
	v_lshl_add_u64 v[38:39], v[6:7], 2, s[10:11]
	v_or_b32_e32 v6, v36, v90
	v_lshl_add_u64 v[62:63], v[62:63], 2, s[10:11]
	v_lshl_add_u64 v[64:65], v[64:65], 2, s[10:11]
	v_lshl_add_u64 v[40:41], v[6:7], 2, s[10:11]
	global_load_dword v157, v[38:39], off
	global_load_dword v179, v[62:63], off
	global_load_dword v187, v[40:41], off
	global_load_dword v188, v[64:65], off
	s_add_i32 s48, s48, 16
	s_add_i32 s2, s2, 16
	s_lshl_b32 s50, s2, 1
	s_lshl_b32 s51, s48, 1
	v_or_b32_e32 v190, s50, v1
	v_or_b32_e32 v191, s51, v2
	s_add_i32 s74, s51, 4
	s_add_i32 s73, s50, 4
	s_add_i32 s75, s50, 8
	s_add_i32 s76, s51, 8
	s_add_i32 s77, s50, 12
	s_add_i32 s79, s50, 16
	s_add_i32 s81, s50, 20
	s_add_i32 s83, s50, 24
	s_add_i32 s50, s50, 28
	v_add_lshl_u32 v6, v190, v3, 10
	v_add_lshl_u32 v40, v191, v34, 10
	v_or_b32_e32 v193, s74, v2
	s_add_i32 s78, s51, 12
	v_or_b32_e32 v192, s73, v1
	v_or_b32_e32 v194, s75, v1
	v_or_b32_e32 v195, s76, v2
	v_or_b32_e32 v196, s77, v1
	v_or_b32_e32 v198, s79, v1
	v_or_b32_e32 v200, s81, v1
	v_or_b32_e32 v202, s83, v1
	v_or_b32_e32 v204, s50, v1
	v_or_b32_e32 v38, v5, v6
	v_or_b32_e32 v6, v36, v40
	v_add_lshl_u32 v42, v193, v34, 10
	v_mov_b32_e32 v39, v7
	s_add_i32 s80, s51, 16
	v_or_b32_e32 v197, s78, v2
	v_add_lshl_u32 v40, v192, v3, 10
	v_add_lshl_u32 v44, v194, v3, 10
	v_add_lshl_u32 v85, v195, v34, 10
	v_add_lshl_u32 v58, v196, v3, 10
	v_add_lshl_u32 v60, v198, v3, 10
	v_add_lshl_u32 v62, v200, v3, 10
	v_add_lshl_u32 v64, v202, v3, 10
	v_add_lshl_u32 v68, v204, v3, 10
	v_lshl_add_u64 v[66:67], v[6:7], 2, s[10:11]
	v_or_b32_e32 v6, v36, v42
	v_mov_b32_e32 v41, v7
	s_add_i32 s82, s51, 20
	v_or_b32_e32 v199, s80, v2
	v_add_lshl_u32 v86, v197, v34, 10
	v_lshl_add_u64 v[38:39], v[38:39], 2, s[10:11]
	v_or_b32_e32 v40, v5, v40
	v_or_b32_e32 v42, v5, v44
	v_or_b32_e32 v44, v5, v58
	v_or_b32_e32 v58, v5, v60
	v_or_b32_e32 v60, v5, v62
	v_or_b32_e32 v62, v5, v64
	v_or_b32_e32 v64, v5, v68
	v_lshl_add_u64 v[68:69], v[6:7], 2, s[10:11]
	v_or_b32_e32 v6, v36, v85
	s_add_i32 s84, s51, 24
	v_or_b32_e32 v201, s82, v2
	v_add_lshl_u32 v87, v199, v34, 10
	v_lshl_add_u64 v[40:41], v[40:41], 2, s[10:11]
	global_load_dword v206, v[66:67], off
	global_load_dword v212, v[38:39], off
	global_load_dword v213, v[68:69], off
	global_load_dword v214, v[40:41], off
	v_lshl_add_u64 v[38:39], v[6:7], 2, s[10:11]
	v_or_b32_e32 v6, v36, v86
	v_mov_b32_e32 v43, v7
	v_mov_b32_e32 v45, v7
	s_add_i32 s51, s51, 28
	v_or_b32_e32 v203, s84, v2
	v_add_lshl_u32 v88, v201, v34, 10
	v_lshl_add_u64 v[40:41], v[6:7], 2, s[10:11]
	v_or_b32_e32 v6, v36, v87
	v_or_b32_e32 v205, s51, v2
	v_add_lshl_u32 v89, v203, v34, 10
	v_lshl_add_u64 v[42:43], v[42:43], 2, s[10:11]
	v_lshl_add_u64 v[44:45], v[44:45], 2, s[10:11]
	global_load_dword v207, v[38:39], off
	global_load_dword v208, v[42:43], off
	global_load_dword v215, v[40:41], off
	global_load_dword v216, v[44:45], off
	v_lshl_add_u64 v[38:39], v[6:7], 2, s[10:11]
	v_or_b32_e32 v6, v36, v88
	v_mov_b32_e32 v59, v7
	v_mov_b32_e32 v61, v7
	v_add_lshl_u32 v90, v205, v34, 10
	v_lshl_add_u64 v[40:41], v[6:7], 2, s[10:11]
	v_or_b32_e32 v6, v36, v89
	v_mov_b32_e32 v63, v7
	v_mov_b32_e32 v65, v7
	v_lshl_add_u64 v[58:59], v[58:59], 2, s[10:11]
	v_lshl_add_u64 v[60:61], v[60:61], 2, s[10:11]
	global_load_dword v209, v[38:39], off
	global_load_dword v210, v[58:59], off
	global_load_dword v217, v[40:41], off
	global_load_dword v218, v[60:61], off
	v_lshl_add_u64 v[38:39], v[6:7], 2, s[10:11]
	v_or_b32_e32 v6, v36, v90
	v_lshl_add_u64 v[62:63], v[62:63], 2, s[10:11]
	v_lshl_add_u64 v[64:65], v[64:65], 2, s[10:11]
	v_lshl_add_u64 v[40:41], v[6:7], 2, s[10:11]
	global_load_dword v189, v[38:39], off
	global_load_dword v211, v[62:63], off
	global_load_dword v219, v[40:41], off
	global_load_dword v221, v[64:65], off
	v_mad_u64_u32 v[38:39], s[50:51], v159, s3, v[4:5]
	v_mad_u64_u32 v[40:41], s[50:51], v158, s3, v[4:5]
	v_mad_u64_u32 v[42:43], s[50:51], v161, s3, v[4:5]
	v_mad_u64_u32 v[44:45], s[50:51], v160, s3, v[4:5]
	v_mad_u64_u32 v[58:59], s[50:51], v163, s3, v[4:5]
	v_mad_u64_u32 v[60:61], s[50:51], v162, s3, v[4:5]
	v_mad_u64_u32 v[62:63], s[50:51], v165, s3, v[4:5]
	v_mad_u64_u32 v[64:65], s[50:51], v164, s3, v[4:5]
	v_mad_u64_u32 v[66:67], s[50:51], v167, s3, v[4:5]
	v_mad_u64_u32 v[68:69], s[50:51], v166, s3, v[4:5]
	v_mad_u64_u32 v[70:71], s[50:51], v169, s3, v[4:5]
	v_mad_u64_u32 v[72:73], s[50:51], v168, s3, v[4:5]
	v_mad_u64_u32 v[74:75], s[50:51], v171, s3, v[4:5]
	v_mad_u64_u32 v[76:77], s[50:51], v170, s3, v[4:5]
	v_mad_u64_u32 v[78:79], s[50:51], v173, s3, v[4:5]
	v_mad_u64_u32 v[80:81], s[50:51], v172, s3, v[4:5]
	s_waitcnt vmcnt(31)
	ds_write_b32 v38, v174
	s_waitcnt vmcnt(30)
	ds_write_b32 v40, v180
	s_waitcnt vmcnt(29)
	ds_write_b32 v42, v181
	s_waitcnt vmcnt(28)
	ds_write_b32 v44, v182
	s_waitcnt vmcnt(27)
	ds_write_b32 v58, v175
	s_waitcnt vmcnt(26)
	ds_write_b32 v60, v176
	s_waitcnt vmcnt(25)
	ds_write_b32 v62, v183
	s_waitcnt vmcnt(24)
	ds_write_b32 v64, v184
	s_waitcnt vmcnt(23)
	ds_write_b32 v66, v177
	s_waitcnt vmcnt(22)
	ds_write_b32 v68, v178
	s_waitcnt vmcnt(21)
	ds_write_b32 v70, v185
	s_waitcnt vmcnt(20)
	ds_write_b32 v72, v186
	s_waitcnt vmcnt(19)
	ds_write_b32 v74, v157
	s_waitcnt vmcnt(18)
	ds_write_b32 v76, v179
	s_waitcnt vmcnt(17)
	ds_write_b32 v78, v187
	s_waitcnt vmcnt(16)
	ds_write_b32 v80, v188
	v_mad_u64_u32 v[38:39], s[50:51], v191, s3, v[4:5]
	v_mad_u64_u32 v[40:41], s[50:51], v190, s3, v[4:5]
	v_mad_u64_u32 v[42:43], s[50:51], v193, s3, v[4:5]
	v_mad_u64_u32 v[44:45], s[50:51], v192, s3, v[4:5]
	v_mad_u64_u32 v[58:59], s[50:51], v195, s3, v[4:5]
	v_mad_u64_u32 v[60:61], s[50:51], v194, s3, v[4:5]
	v_mad_u64_u32 v[62:63], s[50:51], v197, s3, v[4:5]
	v_mad_u64_u32 v[64:65], s[50:51], v196, s3, v[4:5]
	v_mad_u64_u32 v[66:67], s[50:51], v199, s3, v[4:5]
	v_mad_u64_u32 v[68:69], s[50:51], v198, s3, v[4:5]
	v_mad_u64_u32 v[70:71], s[50:51], v201, s3, v[4:5]
	v_mad_u64_u32 v[72:73], s[50:51], v200, s3, v[4:5]
	v_mad_u64_u32 v[74:75], s[50:51], v203, s3, v[4:5]
	v_mad_u64_u32 v[76:77], s[50:51], v202, s3, v[4:5]
	v_mad_u64_u32 v[78:79], s[50:51], v205, s3, v[4:5]
	v_mad_u64_u32 v[80:81], s[50:51], v204, s3, v[4:5]
	s_waitcnt vmcnt(15)
	ds_write_b32 v38, v206
	s_waitcnt vmcnt(14)
	ds_write_b32 v40, v212
	s_waitcnt vmcnt(13)
	ds_write_b32 v42, v213
	s_waitcnt vmcnt(12)
	ds_write_b32 v44, v214
	s_waitcnt vmcnt(11)
	ds_write_b32 v58, v207
	s_waitcnt vmcnt(10)
	ds_write_b32 v60, v208
	s_waitcnt vmcnt(9)
	ds_write_b32 v62, v215
	s_waitcnt vmcnt(8)
	ds_write_b32 v64, v216
	s_waitcnt vmcnt(7)
	ds_write_b32 v66, v209
	s_waitcnt vmcnt(6)
	ds_write_b32 v68, v210
	s_waitcnt vmcnt(5)
	ds_write_b32 v70, v217
	s_waitcnt vmcnt(4)
	ds_write_b32 v72, v218
	s_waitcnt vmcnt(3)
	ds_write_b32 v74, v189
	s_waitcnt vmcnt(2)
	ds_write_b32 v76, v211
	s_waitcnt vmcnt(1)
	ds_write_b32 v78, v219
	s_waitcnt vmcnt(0)
	ds_write_b32 v80, v221
	s_add_i32 s48, s48, 16
	s_add_i32 s2, s2, 16
	s_mov_b32 s49, 0
	s_cmp_lg_u32 s49, 0
	s_waitcnt lgkmcnt(0)
	ds_read2_b32 v[40:41], v50 offset0:33 offset1:41
	ds_read2_b32 v[42:43], v50 offset1:8
	ds_read2_b32 v[44:45], v50 offset0:66 offset1:74
	ds_read2_b32 v[58:59], v50 offset0:99 offset1:107
	ds_read2_b32 v[60:61], v50 offset0:132 offset1:140
	ds_read2_b32 v[62:63], v50 offset0:165 offset1:173
	ds_read2_b32 v[64:65], v50 offset0:198 offset1:206
	ds_read2_b32 v[66:67], v50 offset0:231 offset1:239
	v_lshlrev_b32_e32 v6, 1, v34
	v_or_b32_sdwa v3, v49, v35 dst_sel:DWORD dst_unused:UNUSED_PAD src0_sel:DWORD src1_sel:WORD_0
	v_lshl_add_u64 v[68:69], v[12:13], 0, v[6:7]
	v_lshlrev_b32_e32 v6, 10, v3
	s_waitcnt lgkmcnt(6)
	v_cvt_pk_bf16_f32 v36, v42, v40
	s_waitcnt lgkmcnt(4)
	v_cvt_pk_bf16_f32 v37, v44, v58
	s_waitcnt lgkmcnt(2)
	v_cvt_pk_bf16_f32 v38, v60, v62
	s_waitcnt lgkmcnt(0)
	v_cvt_pk_bf16_f32 v39, v64, v66
	v_lshl_add_u64 v[70:71], v[68:69], 0, v[6:7]
	global_store_dwordx4 v[70:71], v[36:39], off
	v_or_b32_sdwa v3, v51, v35 dst_sel:DWORD dst_unused:UNUSED_PAD src0_sel:DWORD src1_sel:WORD_0
	v_lshlrev_b32_e32 v6, 10, v3
	v_cvt_pk_bf16_f32 v36, v43, v41
	v_cvt_pk_bf16_f32 v37, v45, v59
	v_cvt_pk_bf16_f32 v38, v61, v63
	v_cvt_pk_bf16_f32 v39, v65, v67
	ds_read2_b32 v[42:43], v50 offset0:49 offset1:57
	ds_read2_b32 v[44:45], v50 offset0:16 offset1:24
	ds_read2_b32 v[58:59], v50 offset0:82 offset1:90
	ds_read2_b32 v[60:61], v50 offset0:115 offset1:123
	ds_read2_b32 v[62:63], v50 offset0:148 offset1:156
	ds_read2_b32 v[64:65], v50 offset0:181 offset1:189
	ds_read2_b32 v[66:67], v50 offset0:214 offset1:222
	ds_read2_b32 v[70:71], v50 offset0:247 offset1:255
	v_or_b32_sdwa v3, v52, v35 dst_sel:DWORD dst_unused:UNUSED_PAD src0_sel:DWORD src1_sel:WORD_0
	v_lshl_add_u64 v[40:41], v[68:69], 0, v[6:7]
	v_lshlrev_b32_e32 v6, 10, v3
	v_or_b32_sdwa v3, v53, v35 dst_sel:DWORD dst_unused:UNUSED_PAD src0_sel:DWORD src1_sel:WORD_0
	global_store_dwordx4 v[40:41], v[36:39], off
	v_lshl_add_u64 v[40:41], v[68:69], 0, v[6:7]
	v_lshlrev_b32_e32 v6, 10, v3
	s_waitcnt lgkmcnt(6)
	v_cvt_pk_bf16_f32 v36, v44, v42
	s_waitcnt lgkmcnt(4)
	v_cvt_pk_bf16_f32 v37, v58, v60
	s_waitcnt lgkmcnt(2)
	v_cvt_pk_bf16_f32 v38, v62, v64
	s_waitcnt lgkmcnt(0)
	v_cvt_pk_bf16_f32 v39, v66, v70
	global_store_dwordx4 v[40:41], v[36:39], off
	v_lshl_add_u64 v[34:35], v[68:69], 0, v[6:7]
	s_nop 0
	v_cvt_pk_bf16_f32 v36, v45, v43
	v_cvt_pk_bf16_f32 v37, v59, v61
	v_cvt_pk_bf16_f32 v38, v63, v65
	v_cvt_pk_bf16_f32 v39, v67, v71
	global_store_dwordx4 v[34:35], v[36:39], off
	s_waitcnt lgkmcnt(0)

.LBB0_39:
	s_lshl_b32 s48, s2, 1
	s_lshl_b32 s49, s46, 1
	v_or_b32_e32 v158, s48, v1
	v_or_b32_e32 v159, s49, v2
	s_add_i32 s51, s49, 4
	s_add_i32 s50, s48, 4
	s_add_i32 s73, s48, 8
	s_add_i32 s74, s49, 8
	s_add_i32 s75, s48, 12
	s_add_i32 s77, s48, 16
	s_add_i32 s79, s48, 20
	s_add_i32 s81, s48, 24
	s_add_i32 s48, s48, 28
	v_add_lshl_u32 v6, v158, v3, 10
	v_add_lshl_u32 v40, v159, v34, 10
	v_or_b32_e32 v161, s51, v2
	s_add_i32 s76, s49, 12
	v_or_b32_e32 v160, s50, v1
	v_or_b32_e32 v162, s73, v1
	v_or_b32_e32 v163, s74, v2
	v_or_b32_e32 v164, s75, v1
	v_or_b32_e32 v166, s77, v1
	v_or_b32_e32 v168, s79, v1
	v_or_b32_e32 v170, s81, v1
	v_or_b32_e32 v172, s48, v1
	v_or_b32_e32 v38, v5, v6
	v_or_b32_e32 v6, v36, v40
	v_add_lshl_u32 v42, v161, v34, 10
	v_mov_b32_e32 v39, v7
	s_add_i32 s78, s49, 16
	v_or_b32_e32 v165, s76, v2
	v_add_lshl_u32 v40, v160, v3, 10
	v_add_lshl_u32 v44, v162, v3, 10
	v_add_lshl_u32 v85, v163, v34, 10
	v_add_lshl_u32 v58, v164, v3, 10
	v_add_lshl_u32 v60, v166, v3, 10
	v_add_lshl_u32 v62, v168, v3, 10
	v_add_lshl_u32 v64, v170, v3, 10
	v_add_lshl_u32 v68, v172, v3, 10
	v_lshl_add_u64 v[66:67], v[6:7], 2, s[8:9]
	v_or_b32_e32 v6, v36, v42
	v_mov_b32_e32 v41, v7
	s_add_i32 s80, s49, 20
	v_or_b32_e32 v167, s78, v2
	v_add_lshl_u32 v86, v165, v34, 10
	v_lshl_add_u64 v[38:39], v[38:39], 2, s[8:9]
	v_or_b32_e32 v40, v5, v40
	v_or_b32_e32 v42, v5, v44
	v_or_b32_e32 v44, v5, v58
	v_or_b32_e32 v58, v5, v60
	v_or_b32_e32 v60, v5, v62
	v_or_b32_e32 v62, v5, v64
	v_or_b32_e32 v64, v5, v68
	v_lshl_add_u64 v[68:69], v[6:7], 2, s[8:9]
	v_or_b32_e32 v6, v36, v85
	s_add_i32 s82, s49, 24
	v_or_b32_e32 v169, s80, v2
	v_add_lshl_u32 v87, v167, v34, 10
	v_lshl_add_u64 v[40:41], v[40:41], 2, s[8:9]
	global_load_dword v174, v[66:67], off
	global_load_dword v180, v[38:39], off
	global_load_dword v181, v[68:69], off
	global_load_dword v182, v[40:41], off
	v_lshl_add_u64 v[38:39], v[6:7], 2, s[8:9]
	v_or_b32_e32 v6, v36, v86
	v_mov_b32_e32 v43, v7
	v_mov_b32_e32 v45, v7
	s_add_i32 s49, s49, 28
	v_or_b32_e32 v171, s82, v2
	v_add_lshl_u32 v88, v169, v34, 10
	v_lshl_add_u64 v[40:41], v[6:7], 2, s[8:9]
	v_or_b32_e32 v6, v36, v87
	v_or_b32_e32 v173, s49, v2
	v_add_lshl_u32 v89, v171, v34, 10
	v_lshl_add_u64 v[42:43], v[42:43], 2, s[8:9]
	v_lshl_add_u64 v[44:45], v[44:45], 2, s[8:9]
	global_load_dword v175, v[38:39], off
	global_load_dword v176, v[42:43], off
	global_load_dword v183, v[40:41], off
	global_load_dword v184, v[44:45], off
	v_lshl_add_u64 v[38:39], v[6:7], 2, s[8:9]
	v_or_b32_e32 v6, v36, v88
	v_mov_b32_e32 v59, v7
	v_mov_b32_e32 v61, v7
	v_add_lshl_u32 v90, v173, v34, 10
	v_lshl_add_u64 v[40:41], v[6:7], 2, s[8:9]
	v_or_b32_e32 v6, v36, v89
	v_mov_b32_e32 v63, v7
	v_mov_b32_e32 v65, v7
	v_lshl_add_u64 v[58:59], v[58:59], 2, s[8:9]
	v_lshl_add_u64 v[60:61], v[60:61], 2, s[8:9]
	global_load_dword v177, v[38:39], off
	global_load_dword v178, v[58:59], off
	global_load_dword v185, v[40:41], off
	global_load_dword v186, v[60:61], off
	v_lshl_add_u64 v[38:39], v[6:7], 2, s[8:9]
	v_or_b32_e32 v6, v36, v90
	v_lshl_add_u64 v[62:63], v[62:63], 2, s[8:9]
	v_lshl_add_u64 v[64:65], v[64:65], 2, s[8:9]
	v_lshl_add_u64 v[40:41], v[6:7], 2, s[8:9]
	global_load_dword v157, v[38:39], off
	global_load_dword v179, v[62:63], off
	global_load_dword v187, v[40:41], off
	global_load_dword v188, v[64:65], off
	s_add_i32 s46, s46, 16
	s_add_i32 s2, s2, 16
	s_lshl_b32 s48, s2, 1
	s_lshl_b32 s49, s46, 1
	v_or_b32_e32 v190, s48, v1
	v_or_b32_e32 v191, s49, v2
	s_add_i32 s51, s49, 4
	s_add_i32 s50, s48, 4
	s_add_i32 s73, s48, 8
	s_add_i32 s74, s49, 8
	s_add_i32 s75, s48, 12
	s_add_i32 s77, s48, 16
	s_add_i32 s79, s48, 20
	s_add_i32 s81, s48, 24
	s_add_i32 s48, s48, 28
	v_add_lshl_u32 v6, v190, v3, 10
	v_add_lshl_u32 v40, v191, v34, 10
	v_or_b32_e32 v193, s51, v2
	s_add_i32 s76, s49, 12
	v_or_b32_e32 v192, s50, v1
	v_or_b32_e32 v194, s73, v1
	v_or_b32_e32 v195, s74, v2
	v_or_b32_e32 v196, s75, v1
	v_or_b32_e32 v198, s77, v1
	v_or_b32_e32 v200, s79, v1
	v_or_b32_e32 v202, s81, v1
	v_or_b32_e32 v204, s48, v1
	v_or_b32_e32 v38, v5, v6
	v_or_b32_e32 v6, v36, v40
	v_add_lshl_u32 v42, v193, v34, 10
	v_mov_b32_e32 v39, v7
	s_add_i32 s78, s49, 16
	v_or_b32_e32 v197, s76, v2
	v_add_lshl_u32 v40, v192, v3, 10
	v_add_lshl_u32 v44, v194, v3, 10
	v_add_lshl_u32 v85, v195, v34, 10
	v_add_lshl_u32 v58, v196, v3, 10
	v_add_lshl_u32 v60, v198, v3, 10
	v_add_lshl_u32 v62, v200, v3, 10
	v_add_lshl_u32 v64, v202, v3, 10
	v_add_lshl_u32 v68, v204, v3, 10
	v_lshl_add_u64 v[66:67], v[6:7], 2, s[8:9]
	v_or_b32_e32 v6, v36, v42
	v_mov_b32_e32 v41, v7
	s_add_i32 s80, s49, 20
	v_or_b32_e32 v199, s78, v2
	v_add_lshl_u32 v86, v197, v34, 10
	v_lshl_add_u64 v[38:39], v[38:39], 2, s[8:9]
	v_or_b32_e32 v40, v5, v40
	v_or_b32_e32 v42, v5, v44
	v_or_b32_e32 v44, v5, v58
	v_or_b32_e32 v58, v5, v60
	v_or_b32_e32 v60, v5, v62
	v_or_b32_e32 v62, v5, v64
	v_or_b32_e32 v64, v5, v68
	v_lshl_add_u64 v[68:69], v[6:7], 2, s[8:9]
	v_or_b32_e32 v6, v36, v85
	s_add_i32 s82, s49, 24
	v_or_b32_e32 v201, s80, v2
	v_add_lshl_u32 v87, v199, v34, 10
	v_lshl_add_u64 v[40:41], v[40:41], 2, s[8:9]
	global_load_dword v206, v[66:67], off
	global_load_dword v212, v[38:39], off
	global_load_dword v213, v[68:69], off
	global_load_dword v214, v[40:41], off
	v_lshl_add_u64 v[38:39], v[6:7], 2, s[8:9]
	v_or_b32_e32 v6, v36, v86
	v_mov_b32_e32 v43, v7
	v_mov_b32_e32 v45, v7
	s_add_i32 s49, s49, 28
	v_or_b32_e32 v203, s82, v2
	v_add_lshl_u32 v88, v201, v34, 10
	v_lshl_add_u64 v[40:41], v[6:7], 2, s[8:9]
	v_or_b32_e32 v6, v36, v87
	v_or_b32_e32 v205, s49, v2
	v_add_lshl_u32 v89, v203, v34, 10
	v_lshl_add_u64 v[42:43], v[42:43], 2, s[8:9]
	v_lshl_add_u64 v[44:45], v[44:45], 2, s[8:9]
	global_load_dword v207, v[38:39], off
	global_load_dword v208, v[42:43], off
	global_load_dword v215, v[40:41], off
	global_load_dword v216, v[44:45], off
	v_lshl_add_u64 v[38:39], v[6:7], 2, s[8:9]
	v_or_b32_e32 v6, v36, v88
	v_mov_b32_e32 v59, v7
	v_mov_b32_e32 v61, v7
	v_add_lshl_u32 v90, v205, v34, 10
	v_lshl_add_u64 v[40:41], v[6:7], 2, s[8:9]
	v_or_b32_e32 v6, v36, v89
	v_mov_b32_e32 v63, v7
	v_mov_b32_e32 v65, v7
	v_lshl_add_u64 v[58:59], v[58:59], 2, s[8:9]
	v_lshl_add_u64 v[60:61], v[60:61], 2, s[8:9]
	global_load_dword v209, v[38:39], off
	global_load_dword v210, v[58:59], off
	global_load_dword v217, v[40:41], off
	global_load_dword v218, v[60:61], off
	v_lshl_add_u64 v[38:39], v[6:7], 2, s[8:9]
	v_or_b32_e32 v6, v36, v90
	v_lshl_add_u64 v[62:63], v[62:63], 2, s[8:9]
	v_lshl_add_u64 v[64:65], v[64:65], 2, s[8:9]
	v_lshl_add_u64 v[40:41], v[6:7], 2, s[8:9]
	global_load_dword v189, v[38:39], off
	global_load_dword v211, v[62:63], off
	global_load_dword v219, v[40:41], off
	global_load_dword v221, v[64:65], off
	v_mad_u64_u32 v[38:39], s[48:49], v159, s3, v[4:5]
	v_mad_u64_u32 v[40:41], s[48:49], v158, s3, v[4:5]
	v_mad_u64_u32 v[42:43], s[48:49], v161, s3, v[4:5]
	v_mad_u64_u32 v[44:45], s[48:49], v160, s3, v[4:5]
	v_mad_u64_u32 v[58:59], s[48:49], v163, s3, v[4:5]
	v_mad_u64_u32 v[60:61], s[48:49], v162, s3, v[4:5]
	v_mad_u64_u32 v[62:63], s[48:49], v165, s3, v[4:5]
	v_mad_u64_u32 v[64:65], s[48:49], v164, s3, v[4:5]
	v_mad_u64_u32 v[66:67], s[48:49], v167, s3, v[4:5]
	v_mad_u64_u32 v[68:69], s[48:49], v166, s3, v[4:5]
	v_mad_u64_u32 v[70:71], s[48:49], v169, s3, v[4:5]
	v_mad_u64_u32 v[72:73], s[48:49], v168, s3, v[4:5]
	v_mad_u64_u32 v[74:75], s[48:49], v171, s3, v[4:5]
	v_mad_u64_u32 v[76:77], s[48:49], v170, s3, v[4:5]
	v_mad_u64_u32 v[78:79], s[48:49], v173, s3, v[4:5]
	v_mad_u64_u32 v[80:81], s[48:49], v172, s3, v[4:5]
	s_waitcnt vmcnt(31)
	ds_write_b32 v38, v174
	s_waitcnt vmcnt(30)
	ds_write_b32 v40, v180
	s_waitcnt vmcnt(29)
	ds_write_b32 v42, v181
	s_waitcnt vmcnt(28)
	ds_write_b32 v44, v182
	s_waitcnt vmcnt(27)
	ds_write_b32 v58, v175
	s_waitcnt vmcnt(26)
	ds_write_b32 v60, v176
	s_waitcnt vmcnt(25)
	ds_write_b32 v62, v183
	s_waitcnt vmcnt(24)
	ds_write_b32 v64, v184
	s_waitcnt vmcnt(23)
	ds_write_b32 v66, v177
	s_waitcnt vmcnt(22)
	ds_write_b32 v68, v178
	s_waitcnt vmcnt(21)
	ds_write_b32 v70, v185
	s_waitcnt vmcnt(20)
	ds_write_b32 v72, v186
	s_waitcnt vmcnt(19)
	ds_write_b32 v74, v157
	s_waitcnt vmcnt(18)
	ds_write_b32 v76, v179
	s_waitcnt vmcnt(17)
	ds_write_b32 v78, v187
	s_waitcnt vmcnt(16)
	ds_write_b32 v80, v188
	v_mad_u64_u32 v[38:39], s[48:49], v191, s3, v[4:5]
	v_mad_u64_u32 v[40:41], s[48:49], v190, s3, v[4:5]
	v_mad_u64_u32 v[42:43], s[48:49], v193, s3, v[4:5]
	v_mad_u64_u32 v[44:45], s[48:49], v192, s3, v[4:5]
	v_mad_u64_u32 v[58:59], s[48:49], v195, s3, v[4:5]
	v_mad_u64_u32 v[60:61], s[48:49], v194, s3, v[4:5]
	v_mad_u64_u32 v[62:63], s[48:49], v197, s3, v[4:5]
	v_mad_u64_u32 v[64:65], s[48:49], v196, s3, v[4:5]
	v_mad_u64_u32 v[66:67], s[48:49], v199, s3, v[4:5]
	v_mad_u64_u32 v[68:69], s[48:49], v198, s3, v[4:5]
	v_mad_u64_u32 v[70:71], s[48:49], v201, s3, v[4:5]
	v_mad_u64_u32 v[72:73], s[48:49], v200, s3, v[4:5]
	v_mad_u64_u32 v[74:75], s[48:49], v203, s3, v[4:5]
	v_mad_u64_u32 v[76:77], s[48:49], v202, s3, v[4:5]
	v_mad_u64_u32 v[78:79], s[48:49], v205, s3, v[4:5]
	v_mad_u64_u32 v[80:81], s[48:49], v204, s3, v[4:5]
	s_waitcnt vmcnt(15)
	ds_write_b32 v38, v206
	s_waitcnt vmcnt(14)
	ds_write_b32 v40, v212
	s_waitcnt vmcnt(13)
	ds_write_b32 v42, v213
	s_waitcnt vmcnt(12)
	ds_write_b32 v44, v214
	s_waitcnt vmcnt(11)
	ds_write_b32 v58, v207
	s_waitcnt vmcnt(10)
	ds_write_b32 v60, v208
	s_waitcnt vmcnt(9)
	ds_write_b32 v62, v215
	s_waitcnt vmcnt(8)
	ds_write_b32 v64, v216
	s_waitcnt vmcnt(7)
	ds_write_b32 v66, v209
	s_waitcnt vmcnt(6)
	ds_write_b32 v68, v210
	s_waitcnt vmcnt(5)
	ds_write_b32 v70, v217
	s_waitcnt vmcnt(4)
	ds_write_b32 v72, v218
	s_waitcnt vmcnt(3)
	ds_write_b32 v74, v189
	s_waitcnt vmcnt(2)
	ds_write_b32 v76, v211
	s_waitcnt vmcnt(1)
	ds_write_b32 v78, v219
	s_waitcnt vmcnt(0)
	ds_write_b32 v80, v221
	s_add_i32 s46, s46, 16
	s_add_i32 s2, s2, 16
	s_mov_b32 s47, 0
	s_cmp_lg_u32 s47, 0
	s_waitcnt lgkmcnt(0)
	ds_read2_b32 v[40:41], v50 offset0:33 offset1:41
	ds_read2_b32 v[42:43], v50 offset1:8
	ds_read2_b32 v[44:45], v50 offset0:66 offset1:74
	ds_read2_b32 v[58:59], v50 offset0:99 offset1:107
	ds_read2_b32 v[60:61], v50 offset0:132 offset1:140
	ds_read2_b32 v[62:63], v50 offset0:165 offset1:173
	ds_read2_b32 v[64:65], v50 offset0:198 offset1:206
	ds_read2_b32 v[66:67], v50 offset0:231 offset1:239
	v_lshlrev_b32_e32 v6, 1, v34
	v_or_b32_sdwa v3, v49, v35 dst_sel:DWORD dst_unused:UNUSED_PAD src0_sel:DWORD src1_sel:WORD_0
	v_lshl_add_u64 v[68:69], v[14:15], 0, v[6:7]
	v_lshlrev_b32_e32 v6, 10, v3
	s_waitcnt lgkmcnt(6)
	v_cvt_pk_bf16_f32 v36, v42, v40
	s_waitcnt lgkmcnt(4)
	v_cvt_pk_bf16_f32 v37, v44, v58
	s_waitcnt lgkmcnt(2)
	v_cvt_pk_bf16_f32 v38, v60, v62
	s_waitcnt lgkmcnt(0)
	v_cvt_pk_bf16_f32 v39, v64, v66
	v_lshl_add_u64 v[70:71], v[68:69], 0, v[6:7]
	global_store_dwordx4 v[70:71], v[36:39], off
	v_or_b32_sdwa v3, v51, v35 dst_sel:DWORD dst_unused:UNUSED_PAD src0_sel:DWORD src1_sel:WORD_0
	v_lshlrev_b32_e32 v6, 10, v3
	v_cvt_pk_bf16_f32 v36, v43, v41
	v_cvt_pk_bf16_f32 v37, v45, v59
	v_cvt_pk_bf16_f32 v38, v61, v63
	v_cvt_pk_bf16_f32 v39, v65, v67
	ds_read2_b32 v[42:43], v50 offset0:49 offset1:57
	ds_read2_b32 v[44:45], v50 offset0:16 offset1:24
	ds_read2_b32 v[58:59], v50 offset0:82 offset1:90
	ds_read2_b32 v[60:61], v50 offset0:115 offset1:123
	ds_read2_b32 v[62:63], v50 offset0:148 offset1:156
	ds_read2_b32 v[64:65], v50 offset0:181 offset1:189
	ds_read2_b32 v[66:67], v50 offset0:214 offset1:222
	ds_read2_b32 v[70:71], v50 offset0:247 offset1:255
	v_or_b32_sdwa v3, v52, v35 dst_sel:DWORD dst_unused:UNUSED_PAD src0_sel:DWORD src1_sel:WORD_0
	v_lshl_add_u64 v[40:41], v[68:69], 0, v[6:7]
	v_lshlrev_b32_e32 v6, 10, v3
	v_or_b32_sdwa v3, v53, v35 dst_sel:DWORD dst_unused:UNUSED_PAD src0_sel:DWORD src1_sel:WORD_0
	global_store_dwordx4 v[40:41], v[36:39], off
	v_lshl_add_u64 v[40:41], v[68:69], 0, v[6:7]
	v_lshlrev_b32_e32 v6, 10, v3
	s_waitcnt lgkmcnt(6)
	v_cvt_pk_bf16_f32 v36, v44, v42
	s_waitcnt lgkmcnt(4)
	v_cvt_pk_bf16_f32 v37, v58, v60
	s_waitcnt lgkmcnt(2)
	v_cvt_pk_bf16_f32 v38, v62, v64
	s_waitcnt lgkmcnt(0)
	v_cvt_pk_bf16_f32 v39, v66, v70
	global_store_dwordx4 v[40:41], v[36:39], off
	v_lshl_add_u64 v[34:35], v[68:69], 0, v[6:7]
	s_nop 0
	v_cvt_pk_bf16_f32 v36, v45, v43
	v_cvt_pk_bf16_f32 v37, v59, v61
	v_cvt_pk_bf16_f32 v38, v63, v65
	v_cvt_pk_bf16_f32 v39, v67, v71
	global_store_dwordx4 v[34:35], v[36:39], off
	s_waitcnt lgkmcnt(0)

.LBB0_101:
	s_lshl_b32 s44, s2, 1
	s_lshl_b32 s45, s42, 1
	v_or_b32_e32 v158, s44, v1
	v_or_b32_e32 v159, s45, v2
	s_add_i32 s47, s45, 4
	s_add_i32 s46, s44, 4
	s_add_i32 s48, s44, 8
	s_add_i32 s49, s45, 8
	s_add_i32 s50, s44, 12
	s_add_i32 s73, s44, 16
	s_add_i32 s75, s44, 20
	s_add_i32 s77, s44, 24
	s_add_i32 s44, s44, 28
	v_add_lshl_u32 v6, v158, v3, 10
	v_add_lshl_u32 v40, v159, v34, 10
	v_or_b32_e32 v161, s47, v2
	s_add_i32 s51, s45, 12
	v_or_b32_e32 v160, s46, v1
	v_or_b32_e32 v162, s48, v1
	v_or_b32_e32 v163, s49, v2
	v_or_b32_e32 v164, s50, v1
	v_or_b32_e32 v166, s73, v1
	v_or_b32_e32 v168, s75, v1
	v_or_b32_e32 v170, s77, v1
	v_or_b32_e32 v172, s44, v1
	v_or_b32_e32 v38, v5, v6
	v_or_b32_e32 v6, v36, v40
	v_add_lshl_u32 v42, v161, v34, 10
	v_mov_b32_e32 v39, v7
	s_add_i32 s74, s45, 16
	v_or_b32_e32 v165, s51, v2
	v_add_lshl_u32 v40, v160, v3, 10
	v_add_lshl_u32 v44, v162, v3, 10
	v_add_lshl_u32 v85, v163, v34, 10
	v_add_lshl_u32 v58, v164, v3, 10
	v_add_lshl_u32 v60, v166, v3, 10
	v_add_lshl_u32 v62, v168, v3, 10
	v_add_lshl_u32 v64, v170, v3, 10
	v_add_lshl_u32 v68, v172, v3, 10
	v_lshl_add_u64 v[66:67], v[6:7], 2, s[26:27]
	v_or_b32_e32 v6, v36, v42
	v_mov_b32_e32 v41, v7
	s_add_i32 s76, s45, 20
	v_or_b32_e32 v167, s74, v2
	v_add_lshl_u32 v86, v165, v34, 10
	v_lshl_add_u64 v[38:39], v[38:39], 2, s[26:27]
	v_or_b32_e32 v40, v5, v40
	v_or_b32_e32 v42, v5, v44
	v_or_b32_e32 v44, v5, v58
	v_or_b32_e32 v58, v5, v60
	v_or_b32_e32 v60, v5, v62
	v_or_b32_e32 v62, v5, v64
	v_or_b32_e32 v64, v5, v68
	v_lshl_add_u64 v[68:69], v[6:7], 2, s[26:27]
	v_or_b32_e32 v6, v36, v85
	s_add_i32 s78, s45, 24
	v_or_b32_e32 v169, s76, v2
	v_add_lshl_u32 v87, v167, v34, 10
	v_lshl_add_u64 v[40:41], v[40:41], 2, s[26:27]
	global_load_dword v174, v[66:67], off
	global_load_dword v180, v[38:39], off
	global_load_dword v181, v[68:69], off
	global_load_dword v182, v[40:41], off
	v_lshl_add_u64 v[38:39], v[6:7], 2, s[26:27]
	v_or_b32_e32 v6, v36, v86
	v_mov_b32_e32 v43, v7
	v_mov_b32_e32 v45, v7
	s_add_i32 s45, s45, 28
	v_or_b32_e32 v171, s78, v2
	v_add_lshl_u32 v88, v169, v34, 10
	v_lshl_add_u64 v[40:41], v[6:7], 2, s[26:27]
	v_or_b32_e32 v6, v36, v87
	v_or_b32_e32 v173, s45, v2
	v_add_lshl_u32 v89, v171, v34, 10
	v_lshl_add_u64 v[42:43], v[42:43], 2, s[26:27]
	v_lshl_add_u64 v[44:45], v[44:45], 2, s[26:27]
	global_load_dword v175, v[38:39], off
	global_load_dword v176, v[42:43], off
	global_load_dword v183, v[40:41], off
	global_load_dword v184, v[44:45], off
	v_lshl_add_u64 v[38:39], v[6:7], 2, s[26:27]
	v_or_b32_e32 v6, v36, v88
	v_mov_b32_e32 v59, v7
	v_mov_b32_e32 v61, v7
	v_add_lshl_u32 v90, v173, v34, 10
	v_lshl_add_u64 v[40:41], v[6:7], 2, s[26:27]
	v_or_b32_e32 v6, v36, v89
	v_mov_b32_e32 v63, v7
	v_mov_b32_e32 v65, v7
	v_lshl_add_u64 v[58:59], v[58:59], 2, s[26:27]
	v_lshl_add_u64 v[60:61], v[60:61], 2, s[26:27]
	global_load_dword v177, v[38:39], off
	global_load_dword v178, v[58:59], off
	global_load_dword v185, v[40:41], off
	global_load_dword v186, v[60:61], off
	v_lshl_add_u64 v[38:39], v[6:7], 2, s[26:27]
	v_or_b32_e32 v6, v36, v90
	v_lshl_add_u64 v[62:63], v[62:63], 2, s[26:27]
	v_lshl_add_u64 v[64:65], v[64:65], 2, s[26:27]
	v_lshl_add_u64 v[40:41], v[6:7], 2, s[26:27]
	global_load_dword v157, v[38:39], off
	global_load_dword v179, v[62:63], off
	global_load_dword v187, v[40:41], off
	global_load_dword v188, v[64:65], off
	s_add_i32 s42, s42, 16
	s_add_i32 s2, s2, 16
	s_lshl_b32 s44, s2, 1
	s_lshl_b32 s45, s42, 1
	v_or_b32_e32 v190, s44, v1
	v_or_b32_e32 v191, s45, v2
	s_add_i32 s47, s45, 4
	s_add_i32 s46, s44, 4
	s_add_i32 s48, s44, 8
	s_add_i32 s49, s45, 8
	s_add_i32 s50, s44, 12
	s_add_i32 s73, s44, 16
	s_add_i32 s75, s44, 20
	s_add_i32 s77, s44, 24
	s_add_i32 s44, s44, 28
	v_add_lshl_u32 v6, v190, v3, 10
	v_add_lshl_u32 v40, v191, v34, 10
	v_or_b32_e32 v193, s47, v2
	s_add_i32 s51, s45, 12
	v_or_b32_e32 v192, s46, v1
	v_or_b32_e32 v194, s48, v1
	v_or_b32_e32 v195, s49, v2
	v_or_b32_e32 v196, s50, v1
	v_or_b32_e32 v198, s73, v1
	v_or_b32_e32 v200, s75, v1
	v_or_b32_e32 v202, s77, v1
	v_or_b32_e32 v204, s44, v1
	v_or_b32_e32 v38, v5, v6
	v_or_b32_e32 v6, v36, v40
	v_add_lshl_u32 v42, v193, v34, 10
	v_mov_b32_e32 v39, v7
	s_add_i32 s74, s45, 16
	v_or_b32_e32 v197, s51, v2
	v_add_lshl_u32 v40, v192, v3, 10
	v_add_lshl_u32 v44, v194, v3, 10
	v_add_lshl_u32 v85, v195, v34, 10
	v_add_lshl_u32 v58, v196, v3, 10
	v_add_lshl_u32 v60, v198, v3, 10
	v_add_lshl_u32 v62, v200, v3, 10
	v_add_lshl_u32 v64, v202, v3, 10
	v_add_lshl_u32 v68, v204, v3, 10
	v_lshl_add_u64 v[66:67], v[6:7], 2, s[26:27]
	v_or_b32_e32 v6, v36, v42
	v_mov_b32_e32 v41, v7
	s_add_i32 s76, s45, 20
	v_or_b32_e32 v199, s74, v2
	v_add_lshl_u32 v86, v197, v34, 10
	v_lshl_add_u64 v[38:39], v[38:39], 2, s[26:27]
	v_or_b32_e32 v40, v5, v40
	v_or_b32_e32 v42, v5, v44
	v_or_b32_e32 v44, v5, v58
	v_or_b32_e32 v58, v5, v60
	v_or_b32_e32 v60, v5, v62
	v_or_b32_e32 v62, v5, v64
	v_or_b32_e32 v64, v5, v68
	v_lshl_add_u64 v[68:69], v[6:7], 2, s[26:27]
	v_or_b32_e32 v6, v36, v85
	s_add_i32 s78, s45, 24
	v_or_b32_e32 v201, s76, v2
	v_add_lshl_u32 v87, v199, v34, 10
	v_lshl_add_u64 v[40:41], v[40:41], 2, s[26:27]
	global_load_dword v206, v[66:67], off
	global_load_dword v212, v[38:39], off
	global_load_dword v213, v[68:69], off
	global_load_dword v214, v[40:41], off
	v_lshl_add_u64 v[38:39], v[6:7], 2, s[26:27]
	v_or_b32_e32 v6, v36, v86
	v_mov_b32_e32 v43, v7
	v_mov_b32_e32 v45, v7
	s_add_i32 s45, s45, 28
	v_or_b32_e32 v203, s78, v2
	v_add_lshl_u32 v88, v201, v34, 10
	v_lshl_add_u64 v[40:41], v[6:7], 2, s[26:27]
	v_or_b32_e32 v6, v36, v87
	v_or_b32_e32 v205, s45, v2
	v_add_lshl_u32 v89, v203, v34, 10
	v_lshl_add_u64 v[42:43], v[42:43], 2, s[26:27]
	v_lshl_add_u64 v[44:45], v[44:45], 2, s[26:27]
	global_load_dword v207, v[38:39], off
	global_load_dword v208, v[42:43], off
	global_load_dword v215, v[40:41], off
	global_load_dword v216, v[44:45], off
	v_lshl_add_u64 v[38:39], v[6:7], 2, s[26:27]
	v_or_b32_e32 v6, v36, v88
	v_mov_b32_e32 v59, v7
	v_mov_b32_e32 v61, v7
	v_add_lshl_u32 v90, v205, v34, 10
	v_lshl_add_u64 v[40:41], v[6:7], 2, s[26:27]
	v_or_b32_e32 v6, v36, v89
	v_mov_b32_e32 v63, v7
	v_mov_b32_e32 v65, v7
	v_lshl_add_u64 v[58:59], v[58:59], 2, s[26:27]
	v_lshl_add_u64 v[60:61], v[60:61], 2, s[26:27]
	global_load_dword v209, v[38:39], off
	global_load_dword v210, v[58:59], off
	global_load_dword v217, v[40:41], off
	global_load_dword v218, v[60:61], off
	v_lshl_add_u64 v[38:39], v[6:7], 2, s[26:27]
	v_or_b32_e32 v6, v36, v90
	v_lshl_add_u64 v[62:63], v[62:63], 2, s[26:27]
	v_lshl_add_u64 v[64:65], v[64:65], 2, s[26:27]
	v_lshl_add_u64 v[40:41], v[6:7], 2, s[26:27]
	global_load_dword v189, v[38:39], off
	global_load_dword v211, v[62:63], off
	global_load_dword v219, v[40:41], off
	global_load_dword v221, v[64:65], off
	v_mad_u64_u32 v[38:39], s[44:45], v159, s3, v[4:5]
	v_mad_u64_u32 v[40:41], s[44:45], v158, s3, v[4:5]
	v_mad_u64_u32 v[42:43], s[44:45], v161, s3, v[4:5]
	v_mad_u64_u32 v[44:45], s[44:45], v160, s3, v[4:5]
	v_mad_u64_u32 v[58:59], s[44:45], v163, s3, v[4:5]
	v_mad_u64_u32 v[60:61], s[44:45], v162, s3, v[4:5]
	v_mad_u64_u32 v[62:63], s[44:45], v165, s3, v[4:5]
	v_mad_u64_u32 v[64:65], s[44:45], v164, s3, v[4:5]
	v_mad_u64_u32 v[66:67], s[44:45], v167, s3, v[4:5]
	v_mad_u64_u32 v[68:69], s[44:45], v166, s3, v[4:5]
	v_mad_u64_u32 v[70:71], s[44:45], v169, s3, v[4:5]
	v_mad_u64_u32 v[72:73], s[44:45], v168, s3, v[4:5]
	v_mad_u64_u32 v[74:75], s[44:45], v171, s3, v[4:5]
	v_mad_u64_u32 v[76:77], s[44:45], v170, s3, v[4:5]
	v_mad_u64_u32 v[78:79], s[44:45], v173, s3, v[4:5]
	v_mad_u64_u32 v[80:81], s[44:45], v172, s3, v[4:5]
	s_waitcnt vmcnt(31)
	ds_write_b32 v38, v174
	s_waitcnt vmcnt(30)
	ds_write_b32 v40, v180
	s_waitcnt vmcnt(29)
	ds_write_b32 v42, v181
	s_waitcnt vmcnt(28)
	ds_write_b32 v44, v182
	s_waitcnt vmcnt(27)
	ds_write_b32 v58, v175
	s_waitcnt vmcnt(26)
	ds_write_b32 v60, v176
	s_waitcnt vmcnt(25)
	ds_write_b32 v62, v183
	s_waitcnt vmcnt(24)
	ds_write_b32 v64, v184
	s_waitcnt vmcnt(23)
	ds_write_b32 v66, v177
	s_waitcnt vmcnt(22)
	ds_write_b32 v68, v178
	s_waitcnt vmcnt(21)
	ds_write_b32 v70, v185
	s_waitcnt vmcnt(20)
	ds_write_b32 v72, v186
	s_waitcnt vmcnt(19)
	ds_write_b32 v74, v157
	s_waitcnt vmcnt(18)
	ds_write_b32 v76, v179
	s_waitcnt vmcnt(17)
	ds_write_b32 v78, v187
	s_waitcnt vmcnt(16)
	ds_write_b32 v80, v188
	v_mad_u64_u32 v[38:39], s[44:45], v191, s3, v[4:5]
	v_mad_u64_u32 v[40:41], s[44:45], v190, s3, v[4:5]
	v_mad_u64_u32 v[42:43], s[44:45], v193, s3, v[4:5]
	v_mad_u64_u32 v[44:45], s[44:45], v192, s3, v[4:5]
	v_mad_u64_u32 v[58:59], s[44:45], v195, s3, v[4:5]
	v_mad_u64_u32 v[60:61], s[44:45], v194, s3, v[4:5]
	v_mad_u64_u32 v[62:63], s[44:45], v197, s3, v[4:5]
	v_mad_u64_u32 v[64:65], s[44:45], v196, s3, v[4:5]
	v_mad_u64_u32 v[66:67], s[44:45], v199, s3, v[4:5]
	v_mad_u64_u32 v[68:69], s[44:45], v198, s3, v[4:5]
	v_mad_u64_u32 v[70:71], s[44:45], v201, s3, v[4:5]
	v_mad_u64_u32 v[72:73], s[44:45], v200, s3, v[4:5]
	v_mad_u64_u32 v[74:75], s[44:45], v203, s3, v[4:5]
	v_mad_u64_u32 v[76:77], s[44:45], v202, s3, v[4:5]
	v_mad_u64_u32 v[78:79], s[44:45], v205, s3, v[4:5]
	v_mad_u64_u32 v[80:81], s[44:45], v204, s3, v[4:5]
	s_waitcnt vmcnt(15)
	ds_write_b32 v38, v206
	s_waitcnt vmcnt(14)
	ds_write_b32 v40, v212
	s_waitcnt vmcnt(13)
	ds_write_b32 v42, v213
	s_waitcnt vmcnt(12)
	ds_write_b32 v44, v214
	s_waitcnt vmcnt(11)
	ds_write_b32 v58, v207
	s_waitcnt vmcnt(10)
	ds_write_b32 v60, v208
	s_waitcnt vmcnt(9)
	ds_write_b32 v62, v215
	s_waitcnt vmcnt(8)
	ds_write_b32 v64, v216
	s_waitcnt vmcnt(7)
	ds_write_b32 v66, v209
	s_waitcnt vmcnt(6)
	ds_write_b32 v68, v210
	s_waitcnt vmcnt(5)
	ds_write_b32 v70, v217
	s_waitcnt vmcnt(4)
	ds_write_b32 v72, v218
	s_waitcnt vmcnt(3)
	ds_write_b32 v74, v189
	s_waitcnt vmcnt(2)
	ds_write_b32 v76, v211
	s_waitcnt vmcnt(1)
	ds_write_b32 v78, v219
	s_waitcnt vmcnt(0)
	ds_write_b32 v80, v221
	s_add_i32 s42, s42, 16
	s_add_i32 s2, s2, 16
	s_mov_b32 s43, 0
	s_cmp_lg_u32 s43, 0
	s_waitcnt lgkmcnt(0)
	ds_read2_b32 v[40:41], v50 offset0:33 offset1:41
	ds_read2_b32 v[42:43], v50 offset1:8
	ds_read2_b32 v[44:45], v50 offset0:66 offset1:74
	ds_read2_b32 v[58:59], v50 offset0:99 offset1:107
	ds_read2_b32 v[60:61], v50 offset0:132 offset1:140
	ds_read2_b32 v[62:63], v50 offset0:165 offset1:173
	ds_read2_b32 v[64:65], v50 offset0:198 offset1:206
	ds_read2_b32 v[66:67], v50 offset0:231 offset1:239
	v_or_b32_e32 v3, v35, v49
	v_lshlrev_b32_e32 v6, 1, v34
	v_mul_u32_u24_e32 v3, 0xb00, v3
	v_lshl_add_u64 v[68:69], v[18:19], 0, v[6:7]
	v_lshlrev_b32_e32 v6, 1, v3
	s_waitcnt lgkmcnt(6)
	v_cvt_pk_bf16_f32 v36, v42, v40
	s_waitcnt lgkmcnt(4)
	v_cvt_pk_bf16_f32 v37, v44, v58
	s_waitcnt lgkmcnt(2)
	v_cvt_pk_bf16_f32 v38, v60, v62
	s_waitcnt lgkmcnt(0)
	v_cvt_pk_bf16_f32 v39, v64, v66
	v_lshl_add_u64 v[70:71], v[68:69], 0, v[6:7]
	global_store_dwordx4 v[70:71], v[36:39], off
	v_or_b32_e32 v3, v35, v51
	v_mul_u32_u24_e32 v3, 0xb00, v3
	v_cvt_pk_bf16_f32 v36, v43, v41
	v_cvt_pk_bf16_f32 v37, v45, v59
	v_cvt_pk_bf16_f32 v38, v61, v63
	v_cvt_pk_bf16_f32 v39, v65, v67
	ds_read2_b32 v[42:43], v50 offset0:16 offset1:24
	ds_read2_b32 v[44:45], v50 offset0:49 offset1:57
	ds_read2_b32 v[58:59], v50 offset0:82 offset1:90
	ds_read2_b32 v[60:61], v50 offset0:115 offset1:123
	ds_read2_b32 v[62:63], v50 offset0:148 offset1:156
	ds_read2_b32 v[64:65], v50 offset0:181 offset1:189
	ds_read2_b32 v[66:67], v50 offset0:214 offset1:222
	ds_read2_b32 v[70:71], v50 offset0:247 offset1:255
	v_lshlrev_b32_e32 v6, 1, v3
	v_or_b32_e32 v3, v35, v52
	v_mul_u32_u24_e32 v3, 0xb00, v3
	v_lshl_add_u64 v[40:41], v[68:69], 0, v[6:7]
	v_lshlrev_b32_e32 v6, 1, v3
	v_or_b32_e32 v3, v35, v53
	v_mul_u32_u24_e32 v3, 0xb00, v3
	global_store_dwordx4 v[40:41], v[36:39], off
	v_lshl_add_u64 v[40:41], v[68:69], 0, v[6:7]
	v_lshlrev_b32_e32 v6, 1, v3
	s_waitcnt lgkmcnt(6)
	v_cvt_pk_bf16_f32 v36, v42, v44
	s_waitcnt lgkmcnt(4)
	v_cvt_pk_bf16_f32 v37, v58, v60
	s_waitcnt lgkmcnt(2)
	v_cvt_pk_bf16_f32 v38, v62, v64
	s_waitcnt lgkmcnt(0)
	v_cvt_pk_bf16_f32 v39, v66, v70
	global_store_dwordx4 v[40:41], v[36:39], off
	v_lshl_add_u64 v[34:35], v[68:69], 0, v[6:7]
	s_nop 0
	v_cvt_pk_bf16_f32 v36, v43, v45
	v_cvt_pk_bf16_f32 v37, v59, v61
	v_cvt_pk_bf16_f32 v38, v63, v65
	v_cvt_pk_bf16_f32 v39, v67, v71
	global_store_dwordx4 v[34:35], v[36:39], off
	s_waitcnt lgkmcnt(0)

.LBB0_106:
	s_lshl_b32 s42, s2, 1
	s_lshl_b32 s43, s40, 1
	v_or_b32_e32 v158, s42, v1
	v_or_b32_e32 v159, s43, v2
	s_add_i32 s45, s43, 4
	s_add_i32 s44, s42, 4
	s_add_i32 s46, s42, 8
	s_add_i32 s47, s43, 8
	s_add_i32 s48, s42, 12
	s_add_i32 s50, s42, 16
	s_add_i32 s73, s42, 20
	s_add_i32 s75, s42, 24
	s_add_i32 s42, s42, 28
	v_add_lshl_u32 v6, v158, v3, 10
	v_add_lshl_u32 v40, v159, v34, 10
	v_or_b32_e32 v161, s45, v2
	s_add_i32 s49, s43, 12
	v_or_b32_e32 v160, s44, v1
	v_or_b32_e32 v162, s46, v1
	v_or_b32_e32 v163, s47, v2
	v_or_b32_e32 v164, s48, v1
	v_or_b32_e32 v166, s50, v1
	v_or_b32_e32 v168, s73, v1
	v_or_b32_e32 v170, s75, v1
	v_or_b32_e32 v172, s42, v1
	v_or_b32_e32 v38, v5, v6
	v_or_b32_e32 v6, v36, v40
	v_add_lshl_u32 v42, v161, v34, 10
	v_mov_b32_e32 v39, v7
	s_add_i32 s51, s43, 16
	v_or_b32_e32 v165, s49, v2
	v_add_lshl_u32 v40, v160, v3, 10
	v_add_lshl_u32 v44, v162, v3, 10
	v_add_lshl_u32 v85, v163, v34, 10
	v_add_lshl_u32 v58, v164, v3, 10
	v_add_lshl_u32 v60, v166, v3, 10
	v_add_lshl_u32 v62, v168, v3, 10
	v_add_lshl_u32 v64, v170, v3, 10
	v_add_lshl_u32 v68, v172, v3, 10
	v_lshl_add_u64 v[66:67], v[6:7], 2, s[16:17]
	v_or_b32_e32 v6, v36, v42
	v_mov_b32_e32 v41, v7
	s_add_i32 s74, s43, 20
	v_or_b32_e32 v167, s51, v2
	v_add_lshl_u32 v86, v165, v34, 10
	v_lshl_add_u64 v[38:39], v[38:39], 2, s[16:17]
	v_or_b32_e32 v40, v5, v40
	v_or_b32_e32 v42, v5, v44
	v_or_b32_e32 v44, v5, v58
	v_or_b32_e32 v58, v5, v60
	v_or_b32_e32 v60, v5, v62
	v_or_b32_e32 v62, v5, v64
	v_or_b32_e32 v64, v5, v68
	v_lshl_add_u64 v[68:69], v[6:7], 2, s[16:17]
	v_or_b32_e32 v6, v36, v85
	s_add_i32 s76, s43, 24
	v_or_b32_e32 v169, s74, v2
	v_add_lshl_u32 v87, v167, v34, 10
	v_lshl_add_u64 v[40:41], v[40:41], 2, s[16:17]
	global_load_dword v174, v[66:67], off
	global_load_dword v180, v[38:39], off
	global_load_dword v181, v[68:69], off
	global_load_dword v182, v[40:41], off
	v_lshl_add_u64 v[38:39], v[6:7], 2, s[16:17]
	v_or_b32_e32 v6, v36, v86
	v_mov_b32_e32 v43, v7
	v_mov_b32_e32 v45, v7
	s_add_i32 s43, s43, 28
	v_or_b32_e32 v171, s76, v2
	v_add_lshl_u32 v88, v169, v34, 10
	v_lshl_add_u64 v[40:41], v[6:7], 2, s[16:17]
	v_or_b32_e32 v6, v36, v87
	v_or_b32_e32 v173, s43, v2
	v_add_lshl_u32 v89, v171, v34, 10
	v_lshl_add_u64 v[42:43], v[42:43], 2, s[16:17]
	v_lshl_add_u64 v[44:45], v[44:45], 2, s[16:17]
	global_load_dword v175, v[38:39], off
	global_load_dword v176, v[42:43], off
	global_load_dword v183, v[40:41], off
	global_load_dword v184, v[44:45], off
	v_lshl_add_u64 v[38:39], v[6:7], 2, s[16:17]
	v_or_b32_e32 v6, v36, v88
	v_mov_b32_e32 v59, v7
	v_mov_b32_e32 v61, v7
	v_add_lshl_u32 v90, v173, v34, 10
	v_lshl_add_u64 v[40:41], v[6:7], 2, s[16:17]
	v_or_b32_e32 v6, v36, v89
	v_mov_b32_e32 v63, v7
	v_mov_b32_e32 v65, v7
	v_lshl_add_u64 v[58:59], v[58:59], 2, s[16:17]
	v_lshl_add_u64 v[60:61], v[60:61], 2, s[16:17]
	global_load_dword v177, v[38:39], off
	global_load_dword v178, v[58:59], off
	global_load_dword v185, v[40:41], off
	global_load_dword v186, v[60:61], off
	v_lshl_add_u64 v[38:39], v[6:7], 2, s[16:17]
	v_or_b32_e32 v6, v36, v90
	v_lshl_add_u64 v[62:63], v[62:63], 2, s[16:17]
	v_lshl_add_u64 v[64:65], v[64:65], 2, s[16:17]
	v_lshl_add_u64 v[40:41], v[6:7], 2, s[16:17]
	global_load_dword v157, v[38:39], off
	global_load_dword v179, v[62:63], off
	global_load_dword v187, v[40:41], off
	global_load_dword v188, v[64:65], off
	s_add_i32 s40, s40, 16
	s_add_i32 s2, s2, 16
	s_lshl_b32 s42, s2, 1
	s_lshl_b32 s43, s40, 1
	v_or_b32_e32 v190, s42, v1
	v_or_b32_e32 v191, s43, v2
	s_add_i32 s45, s43, 4
	s_add_i32 s44, s42, 4
	s_add_i32 s46, s42, 8
	s_add_i32 s47, s43, 8
	s_add_i32 s48, s42, 12
	s_add_i32 s50, s42, 16
	s_add_i32 s73, s42, 20
	s_add_i32 s75, s42, 24
	s_add_i32 s42, s42, 28
	v_add_lshl_u32 v6, v190, v3, 10
	v_add_lshl_u32 v40, v191, v34, 10
	v_or_b32_e32 v193, s45, v2
	s_add_i32 s49, s43, 12
	v_or_b32_e32 v192, s44, v1
	v_or_b32_e32 v194, s46, v1
	v_or_b32_e32 v195, s47, v2
	v_or_b32_e32 v196, s48, v1
	v_or_b32_e32 v198, s50, v1
	v_or_b32_e32 v200, s73, v1
	v_or_b32_e32 v202, s75, v1
	v_or_b32_e32 v204, s42, v1
	v_or_b32_e32 v38, v5, v6
	v_or_b32_e32 v6, v36, v40
	v_add_lshl_u32 v42, v193, v34, 10
	v_mov_b32_e32 v39, v7
	s_add_i32 s51, s43, 16
	v_or_b32_e32 v197, s49, v2
	v_add_lshl_u32 v40, v192, v3, 10
	v_add_lshl_u32 v44, v194, v3, 10
	v_add_lshl_u32 v85, v195, v34, 10
	v_add_lshl_u32 v58, v196, v3, 10
	v_add_lshl_u32 v60, v198, v3, 10
	v_add_lshl_u32 v62, v200, v3, 10
	v_add_lshl_u32 v64, v202, v3, 10
	v_add_lshl_u32 v68, v204, v3, 10
	v_lshl_add_u64 v[66:67], v[6:7], 2, s[16:17]
	v_or_b32_e32 v6, v36, v42
	v_mov_b32_e32 v41, v7
	s_add_i32 s74, s43, 20
	v_or_b32_e32 v199, s51, v2
	v_add_lshl_u32 v86, v197, v34, 10
	v_lshl_add_u64 v[38:39], v[38:39], 2, s[16:17]
	v_or_b32_e32 v40, v5, v40
	v_or_b32_e32 v42, v5, v44
	v_or_b32_e32 v44, v5, v58
	v_or_b32_e32 v58, v5, v60
	v_or_b32_e32 v60, v5, v62
	v_or_b32_e32 v62, v5, v64
	v_or_b32_e32 v64, v5, v68
	v_lshl_add_u64 v[68:69], v[6:7], 2, s[16:17]
	v_or_b32_e32 v6, v36, v85
	s_add_i32 s76, s43, 24
	v_or_b32_e32 v201, s74, v2
	v_add_lshl_u32 v87, v199, v34, 10
	v_lshl_add_u64 v[40:41], v[40:41], 2, s[16:17]
	global_load_dword v206, v[66:67], off
	global_load_dword v212, v[38:39], off
	global_load_dword v213, v[68:69], off
	global_load_dword v214, v[40:41], off
	v_lshl_add_u64 v[38:39], v[6:7], 2, s[16:17]
	v_or_b32_e32 v6, v36, v86
	v_mov_b32_e32 v43, v7
	v_mov_b32_e32 v45, v7
	s_add_i32 s43, s43, 28
	v_or_b32_e32 v203, s76, v2
	v_add_lshl_u32 v88, v201, v34, 10
	v_lshl_add_u64 v[40:41], v[6:7], 2, s[16:17]
	v_or_b32_e32 v6, v36, v87
	v_or_b32_e32 v205, s43, v2
	v_add_lshl_u32 v89, v203, v34, 10
	v_lshl_add_u64 v[42:43], v[42:43], 2, s[16:17]
	v_lshl_add_u64 v[44:45], v[44:45], 2, s[16:17]
	global_load_dword v207, v[38:39], off
	global_load_dword v208, v[42:43], off
	global_load_dword v215, v[40:41], off
	global_load_dword v216, v[44:45], off
	v_lshl_add_u64 v[38:39], v[6:7], 2, s[16:17]
	v_or_b32_e32 v6, v36, v88
	v_mov_b32_e32 v59, v7
	v_mov_b32_e32 v61, v7
	v_add_lshl_u32 v90, v205, v34, 10
	v_lshl_add_u64 v[40:41], v[6:7], 2, s[16:17]
	v_or_b32_e32 v6, v36, v89
	v_mov_b32_e32 v63, v7
	v_mov_b32_e32 v65, v7
	v_lshl_add_u64 v[58:59], v[58:59], 2, s[16:17]
	v_lshl_add_u64 v[60:61], v[60:61], 2, s[16:17]
	global_load_dword v209, v[38:39], off
	global_load_dword v210, v[58:59], off
	global_load_dword v217, v[40:41], off
	global_load_dword v218, v[60:61], off
	v_lshl_add_u64 v[38:39], v[6:7], 2, s[16:17]
	v_or_b32_e32 v6, v36, v90
	v_lshl_add_u64 v[62:63], v[62:63], 2, s[16:17]
	v_lshl_add_u64 v[64:65], v[64:65], 2, s[16:17]
	v_lshl_add_u64 v[40:41], v[6:7], 2, s[16:17]
	global_load_dword v189, v[38:39], off
	global_load_dword v211, v[62:63], off
	global_load_dword v219, v[40:41], off
	global_load_dword v221, v[64:65], off
	v_mad_u64_u32 v[38:39], s[42:43], v159, s3, v[4:5]
	v_mad_u64_u32 v[40:41], s[42:43], v158, s3, v[4:5]
	v_mad_u64_u32 v[42:43], s[42:43], v161, s3, v[4:5]
	v_mad_u64_u32 v[44:45], s[42:43], v160, s3, v[4:5]
	v_mad_u64_u32 v[58:59], s[42:43], v163, s3, v[4:5]
	v_mad_u64_u32 v[60:61], s[42:43], v162, s3, v[4:5]
	v_mad_u64_u32 v[62:63], s[42:43], v165, s3, v[4:5]
	v_mad_u64_u32 v[64:65], s[42:43], v164, s3, v[4:5]
	v_mad_u64_u32 v[66:67], s[42:43], v167, s3, v[4:5]
	v_mad_u64_u32 v[68:69], s[42:43], v166, s3, v[4:5]
	v_mad_u64_u32 v[70:71], s[42:43], v169, s3, v[4:5]
	v_mad_u64_u32 v[72:73], s[42:43], v168, s3, v[4:5]
	v_mad_u64_u32 v[74:75], s[42:43], v171, s3, v[4:5]
	v_mad_u64_u32 v[76:77], s[42:43], v170, s3, v[4:5]
	v_mad_u64_u32 v[78:79], s[42:43], v173, s3, v[4:5]
	v_mad_u64_u32 v[80:81], s[42:43], v172, s3, v[4:5]
	s_waitcnt vmcnt(31)
	ds_write_b32 v38, v174
	s_waitcnt vmcnt(30)
	ds_write_b32 v40, v180
	s_waitcnt vmcnt(29)
	ds_write_b32 v42, v181
	s_waitcnt vmcnt(28)
	ds_write_b32 v44, v182
	s_waitcnt vmcnt(27)
	ds_write_b32 v58, v175
	s_waitcnt vmcnt(26)
	ds_write_b32 v60, v176
	s_waitcnt vmcnt(25)
	ds_write_b32 v62, v183
	s_waitcnt vmcnt(24)
	ds_write_b32 v64, v184
	s_waitcnt vmcnt(23)
	ds_write_b32 v66, v177
	s_waitcnt vmcnt(22)
	ds_write_b32 v68, v178
	s_waitcnt vmcnt(21)
	ds_write_b32 v70, v185
	s_waitcnt vmcnt(20)
	ds_write_b32 v72, v186
	s_waitcnt vmcnt(19)
	ds_write_b32 v74, v157
	s_waitcnt vmcnt(18)
	ds_write_b32 v76, v179
	s_waitcnt vmcnt(17)
	ds_write_b32 v78, v187
	s_waitcnt vmcnt(16)
	ds_write_b32 v80, v188
	v_mad_u64_u32 v[38:39], s[42:43], v191, s3, v[4:5]
	v_mad_u64_u32 v[40:41], s[42:43], v190, s3, v[4:5]
	v_mad_u64_u32 v[42:43], s[42:43], v193, s3, v[4:5]
	v_mad_u64_u32 v[44:45], s[42:43], v192, s3, v[4:5]
	v_mad_u64_u32 v[58:59], s[42:43], v195, s3, v[4:5]
	v_mad_u64_u32 v[60:61], s[42:43], v194, s3, v[4:5]
	v_mad_u64_u32 v[62:63], s[42:43], v197, s3, v[4:5]
	v_mad_u64_u32 v[64:65], s[42:43], v196, s3, v[4:5]
	v_mad_u64_u32 v[66:67], s[42:43], v199, s3, v[4:5]
	v_mad_u64_u32 v[68:69], s[42:43], v198, s3, v[4:5]
	v_mad_u64_u32 v[70:71], s[42:43], v201, s3, v[4:5]
	v_mad_u64_u32 v[72:73], s[42:43], v200, s3, v[4:5]
	v_mad_u64_u32 v[74:75], s[42:43], v203, s3, v[4:5]
	v_mad_u64_u32 v[76:77], s[42:43], v202, s3, v[4:5]
	v_mad_u64_u32 v[78:79], s[42:43], v205, s3, v[4:5]
	v_mad_u64_u32 v[80:81], s[42:43], v204, s3, v[4:5]
	s_waitcnt vmcnt(15)
	ds_write_b32 v38, v206
	s_waitcnt vmcnt(14)
	ds_write_b32 v40, v212
	s_waitcnt vmcnt(13)
	ds_write_b32 v42, v213
	s_waitcnt vmcnt(12)
	ds_write_b32 v44, v214
	s_waitcnt vmcnt(11)
	ds_write_b32 v58, v207
	s_waitcnt vmcnt(10)
	ds_write_b32 v60, v208
	s_waitcnt vmcnt(9)
	ds_write_b32 v62, v215
	s_waitcnt vmcnt(8)
	ds_write_b32 v64, v216
	s_waitcnt vmcnt(7)
	ds_write_b32 v66, v209
	s_waitcnt vmcnt(6)
	ds_write_b32 v68, v210
	s_waitcnt vmcnt(5)
	ds_write_b32 v70, v217
	s_waitcnt vmcnt(4)
	ds_write_b32 v72, v218
	s_waitcnt vmcnt(3)
	ds_write_b32 v74, v189
	s_waitcnt vmcnt(2)
	ds_write_b32 v76, v211
	s_waitcnt vmcnt(1)
	ds_write_b32 v78, v219
	s_waitcnt vmcnt(0)
	ds_write_b32 v80, v221
	s_add_i32 s40, s40, 16
	s_add_i32 s2, s2, 16
	s_mov_b32 s41, 0
	s_cmp_lg_u32 s41, 0
	s_waitcnt lgkmcnt(0)
	ds_read2_b32 v[40:41], v50 offset0:33 offset1:41
	ds_read2_b32 v[42:43], v50 offset1:8
	ds_read2_b32 v[44:45], v50 offset0:66 offset1:74
	ds_read2_b32 v[58:59], v50 offset0:99 offset1:107
	ds_read2_b32 v[60:61], v50 offset0:132 offset1:140
	ds_read2_b32 v[62:63], v50 offset0:165 offset1:173
	ds_read2_b32 v[64:65], v50 offset0:198 offset1:206
	ds_read2_b32 v[66:67], v50 offset0:231 offset1:239
	v_or_b32_e32 v3, v35, v49
	v_lshlrev_b32_e32 v6, 1, v34
	v_mul_u32_u24_e32 v3, 0xb00, v3
	v_lshl_add_u64 v[68:69], v[20:21], 0, v[6:7]
	v_lshlrev_b32_e32 v6, 1, v3
	s_waitcnt lgkmcnt(6)
	v_cvt_pk_bf16_f32 v36, v42, v40
	s_waitcnt lgkmcnt(4)
	v_cvt_pk_bf16_f32 v37, v44, v58
	s_waitcnt lgkmcnt(2)
	v_cvt_pk_bf16_f32 v38, v60, v62
	s_waitcnt lgkmcnt(0)
	v_cvt_pk_bf16_f32 v39, v64, v66
	v_lshl_add_u64 v[70:71], v[68:69], 0, v[6:7]
	global_store_dwordx4 v[70:71], v[36:39], off
	v_or_b32_e32 v3, v35, v51
	v_mul_u32_u24_e32 v3, 0xb00, v3
	v_cvt_pk_bf16_f32 v36, v43, v41
	v_cvt_pk_bf16_f32 v37, v45, v59
	v_cvt_pk_bf16_f32 v38, v61, v63
	v_cvt_pk_bf16_f32 v39, v65, v67
	ds_read2_b32 v[42:43], v50 offset0:16 offset1:24
	ds_read2_b32 v[44:45], v50 offset0:49 offset1:57
	ds_read2_b32 v[58:59], v50 offset0:82 offset1:90
	ds_read2_b32 v[60:61], v50 offset0:115 offset1:123
	ds_read2_b32 v[62:63], v50 offset0:148 offset1:156
	ds_read2_b32 v[64:65], v50 offset0:181 offset1:189
	ds_read2_b32 v[66:67], v50 offset0:214 offset1:222
	ds_read2_b32 v[70:71], v50 offset0:247 offset1:255
	v_lshlrev_b32_e32 v6, 1, v3
	v_or_b32_e32 v3, v35, v52
	v_mul_u32_u24_e32 v3, 0xb00, v3
	v_lshl_add_u64 v[40:41], v[68:69], 0, v[6:7]
	v_lshlrev_b32_e32 v6, 1, v3
	v_or_b32_e32 v3, v35, v53
	v_mul_u32_u24_e32 v3, 0xb00, v3
	global_store_dwordx4 v[40:41], v[36:39], off
	v_lshl_add_u64 v[40:41], v[68:69], 0, v[6:7]
	v_lshlrev_b32_e32 v6, 1, v3
	s_waitcnt lgkmcnt(6)
	v_cvt_pk_bf16_f32 v36, v42, v44
	s_waitcnt lgkmcnt(4)
	v_cvt_pk_bf16_f32 v37, v58, v60
	s_waitcnt lgkmcnt(2)
	v_cvt_pk_bf16_f32 v38, v62, v64
	s_waitcnt lgkmcnt(0)
	v_cvt_pk_bf16_f32 v39, v66, v70
	global_store_dwordx4 v[40:41], v[36:39], off
	v_lshl_add_u64 v[34:35], v[68:69], 0, v[6:7]
	s_nop 0
	v_cvt_pk_bf16_f32 v36, v43, v45
	v_cvt_pk_bf16_f32 v37, v59, v61
	v_cvt_pk_bf16_f32 v38, v63, v65
	v_cvt_pk_bf16_f32 v39, v67, v71
	global_store_dwordx4 v[34:35], v[36:39], off
	s_waitcnt lgkmcnt(0)
